# in-proj and ffn-up K-loops: LDS-DMA loads in SGPR-base + 32-bit VGPR-offset form (address VALU after each barrier replaced by SALU)
# baseline (speedup 1.0000x reference)
; #define PG8_STAGE(bufoff, gbase, voff) do { _Pragma("unroll") for (int _i = 0; _i < 2; ++_i) \
;         __builtin_amdgcn_global_load_lds((const unsigned*)((const char*)(gbase) + (voff)[_i]), (LAS unsigned*)(lds + (bufoff) + ldsw + _i * 8192), 16, 0, 0); } while (0)
; #define PG8_LDA(dst, b, h) do { _Pragma("unroll") for (int m = 0; m < 4; ++m) _Pragma("unroll") for (int k = 0; k < 2; ++k) dst[m][k] = *(const LAS bf16x8*)(lds + PG8_SA(b, h) + aoff + m * 2048 + k * 1024); } while (0)
; #define PG8_LDB(dst, b, h) do { _Pragma("unroll") for (int n = 0; n < 2; ++n) _Pragma("unroll") for (int k = 0; k < 2; ++k) dst[n][k] = *(const LAS bf16x8*)(lds + PG8_SB(b, h) + boff + n * 2048 + k * 1024); } while (0)
; #define PG8_MMA(ai, bj, At, Bt) do { __builtin_amdgcn_s_setprio(2); _Pragma("unroll") for (int m = 0; m < 4; ++m) _Pragma("unroll") for (int n = 0; n < 2; ++n) _Pragma("unroll") for (int k = 0; k < 2; ++k) \
;         acc[ai][bj][m][n] = __builtin_amdgcn_mfma_f32_16x16x32_bf16(Bt[n][k], At[m][k], acc[ai][bj][m][n], 0, 0, 0); __builtin_amdgcn_s_setprio(0); } while (0)
; #define PG8_WAIT_V(n) asm volatile("s_waitcnt vmcnt(" #n ")" ::: "memory")
; #define PG8_WAIT_L(n) asm volatile("s_waitcnt lgkmcnt(" #n ")" ::: "memory")
; #define PG8_BAR __builtin_amdgcn_s_barrier()
; #define PG8_SCHED __builtin_amdgcn_sched_barrier(0)
; template <class Epi>
; __device__ __forceinline__ void gemm_phase(const Lt& lt, LAS unsigned char* lds, const Gemm g, const StaticOrder& S, const Epi& E) {
;     ...
;             PG8_LDB(B0, 0, 0); PG8_LDB(B1, 0, 1); PG8_SCHED; PG8_LDA(At, 0, 0); PG8_STAGE(PG8_SA(1, 1), a1 + hstep, voffA);
;             PG8_WAIT_V(8); PG8_WAIT_L(0); PG8_BAR; PG8_MMA(0, 0, At, B0); PG8_MMA(0, 1, At, B1); PG8_BAR; PG8_SCHED;
;             PG8_LDA(At, 0, 1); PG8_STAGE(PG8_SB(0, 0), b2, voffB); PG8_STAGE(PG8_SB(0, 1), b2 + hstep, voffB); PG8_STAGE(PG8_SA(0, 0), a2, voffA);
;             PG8_WAIT_V(8); PG8_WAIT_L(0); PG8_BAR; PG8_MMA(1, 0, At, B0); PG8_MMA(1, 1, At, B1); PG8_BAR; PG8_SCHED;
.LBB0_78:
	s_add_u32 s48, s42, s4
	s_addc_u32 s49, s43, s5
	s_add_u32 s48, s48, 0x100
	s_addc_u32 s49, s49, 0
	s_add_u32 s69, s64, s4
	s_addc_u32 s70, s65, s5
	s_add_i32 s71, 0, 0x10000
	s_cmpk_eq_i32 s4, 0xf00
	s_cselect_b32 s51, s41, s49
	s_cselect_b32 s50, s66, s48
	v_add_u32_e32 v148, s71, v152
	s_cselect_b32 s49, s37, s70
	s_cselect_b32 s48, s67, s69
	s_add_i32 s69, 0, 0x14000
	ds_read_b128 v[144:147], v148
	ds_read_b128 v[156:159], v148 offset:1024
	ds_read_b128 v[160:163], v148 offset:2048
	ds_read_b128 v[164:167], v148 offset:3072
	v_add_u32_e32 v148, s69, v152
	ds_read_b128 v[168:171], v148
	ds_read_b128 v[172:175], v148 offset:1024
	ds_read_b128 v[176:179], v148 offset:2048
	ds_read_b128 v[180:183], v148 offset:3072
	s_add_u32 s72, s42, s4
	s_addc_u32 s73, s43, s5
	s_add_u32 s72, s72, 0x80080
	s_addc_u32 s73, s73, 0
	s_add_i32 m0, s29, 0xc000
	ds_read_b128 v[184:187], v155
	ds_read_b128 v[188:191], v155 offset:1024
	ds_read_b128 v[192:195], v155 offset:2048
	ds_read_b128 v[210:213], v155 offset:3072
	ds_read_b128 v[214:217], v155 offset:4096
	ds_read_b128 v[218:221], v155 offset:5120
	ds_read_b128 v[222:225], v155 offset:6144
	ds_read_b128 v[226:229], v155 offset:7168
	global_load_lds_dwordx4 v136, s[72:73]
	s_add_i32 m0, s29, 0xe000
	s_nop 0
	global_load_lds_dwordx4 v138, s[72:73]
	s_waitcnt vmcnt(8)
	s_waitcnt lgkmcnt(0)
	s_barrier
	s_setprio 2
	s_waitcnt lgkmcnt(0)
	v_mfma_f32_16x16x32_bf16 v[128:131], v[144:147], v[184:187], v[128:131]
	v_mfma_f32_16x16x32_bf16 v[124:127], v[160:163], v[184:187], v[124:127]
	v_mfma_f32_16x16x32_bf16 v[120:123], v[144:147], v[192:195], v[120:123]
	v_mfma_f32_16x16x32_bf16 v[116:119], v[160:163], v[192:195], v[116:119]
	v_mfma_f32_16x16x32_bf16 v[112:115], v[144:147], v[214:217], v[112:115]
	v_mfma_f32_16x16x32_bf16 v[108:111], v[160:163], v[214:217], v[108:111]
	v_mfma_f32_16x16x32_bf16 v[104:107], v[144:147], v[222:225], v[104:107]
	v_mfma_f32_16x16x32_bf16 v[100:103], v[160:163], v[222:225], v[100:103]
	v_mfma_f32_16x16x32_bf16 v[128:131], v[156:159], v[188:191], v[128:131]
	v_mfma_f32_16x16x32_bf16 v[124:127], v[164:167], v[188:191], v[124:127]
	v_mfma_f32_16x16x32_bf16 v[120:123], v[156:159], v[210:213], v[120:123]
	v_mfma_f32_16x16x32_bf16 v[116:119], v[164:167], v[210:213], v[116:119]
	v_mfma_f32_16x16x32_bf16 v[112:115], v[156:159], v[218:221], v[112:115]
	v_mfma_f32_16x16x32_bf16 v[108:111], v[164:167], v[218:221], v[108:111]
	v_mfma_f32_16x16x32_bf16 v[104:107], v[156:159], v[226:229], v[104:107]
	v_mfma_f32_16x16x32_bf16 v[100:103], v[164:167], v[226:229], v[100:103]
	s_setprio 0
	s_setprio 2
	v_mfma_f32_16x16x32_bf16 v[96:99], v[168:171], v[184:187], v[96:99]
	v_mfma_f32_16x16x32_bf16 v[92:95], v[176:179], v[184:187], v[92:95]
	v_mfma_f32_16x16x32_bf16 v[88:91], v[168:171], v[192:195], v[88:91]
	v_mfma_f32_16x16x32_bf16 v[84:87], v[176:179], v[192:195], v[84:87]
	v_mfma_f32_16x16x32_bf16 v[80:83], v[168:171], v[214:217], v[80:83]
	v_mfma_f32_16x16x32_bf16 v[76:79], v[176:179], v[214:217], v[76:79]
	v_mfma_f32_16x16x32_bf16 v[72:75], v[168:171], v[222:225], v[72:75]
	v_mfma_f32_16x16x32_bf16 v[68:71], v[176:179], v[222:225], v[68:71]
	v_mfma_f32_16x16x32_bf16 v[96:99], v[172:175], v[188:191], v[96:99]
	v_mfma_f32_16x16x32_bf16 v[92:95], v[180:183], v[188:191], v[92:95]
	v_mfma_f32_16x16x32_bf16 v[88:91], v[172:175], v[210:213], v[88:91]
	v_mfma_f32_16x16x32_bf16 v[84:87], v[180:183], v[210:213], v[84:87]
	v_mfma_f32_16x16x32_bf16 v[80:83], v[172:175], v[218:221], v[80:83]
	v_mfma_f32_16x16x32_bf16 v[76:79], v[180:183], v[218:221], v[76:79]
	v_mfma_f32_16x16x32_bf16 v[72:75], v[172:175], v[226:229], v[72:75]
	v_mfma_f32_16x16x32_bf16 v[68:71], v[180:183], v[226:229], v[68:71]
	s_setprio 0
	s_barrier
	s_add_i32 s70, s71, s57
	s_mov_b32 m0, s70
	ds_read_b128 v[184:187], v155 offset:16384
	ds_read_b128 v[188:191], v155 offset:17408
	ds_read_b128 v[192:195], v155 offset:18432
	ds_read_b128 v[210:213], v155 offset:19456
	ds_read_b128 v[214:217], v155 offset:20480
	ds_read_b128 v[218:221], v155 offset:21504
	ds_read_b128 v[222:225], v155 offset:22528
	ds_read_b128 v[226:229], v155 offset:23552
	global_load_lds_dwordx4 v2, s[48:49]
	s_add_i32 m0, s70, 0x2000
	s_add_u32 s70, s48, 0x80000
	s_addc_u32 s71, s49, 0
	s_add_i32 s69, s69, s57
	global_load_lds_dwordx4 v134, s[48:49]
	s_mov_b32 m0, s69
	s_add_u32 s78, s50, s12
	s_addc_u32 s79, s51, s13
	global_load_lds_dwordx4 v2, s[70:71]
	s_add_i32 m0, s69, 0x2000
	s_nop 0
	global_load_lds_dwordx4 v134, s[70:71]
	s_mov_b32 m0, s29
	s_nop 0
	global_load_lds_dwordx4 v0, s[50:51]
	s_mov_b32 m0, s31
	s_nop 0
	global_load_lds_dwordx4 v132, s[50:51]
	s_waitcnt vmcnt(8)
	s_waitcnt lgkmcnt(0)
	s_barrier
; #define PG8_STAGE(bufoff, gbase, voff) do { _Pragma("unroll") for (int _i = 0; _i < 2; ++_i) \
;         __builtin_amdgcn_global_load_lds((const unsigned*)((const char*)(gbase) + (voff)[_i]), (LAS unsigned*)(lds + (bufoff) + ldsw + _i * 8192), 16, 0, 0); } while (0)
; #define PG8_LDA(dst, b, h) do { _Pragma("unroll") for (int m = 0; m < 4; ++m) _Pragma("unroll") for (int k = 0; k < 2; ++k) dst[m][k] = *(const LAS bf16x8*)(lds + PG8_SA(b, h) + aoff + m * 2048 + k * 1024); } while (0)
; #define PG8_LDB(dst, b, h) do { _Pragma("unroll") for (int n = 0; n < 2; ++n) _Pragma("unroll") for (int k = 0; k < 2; ++k) dst[n][k] = *(const LAS bf16x8*)(lds + PG8_SB(b, h) + boff + n * 2048 + k * 1024); } while (0)
; #define PG8_MMA(ai, bj, At, Bt) do { __builtin_amdgcn_s_setprio(2); _Pragma("unroll") for (int m = 0; m < 4; ++m) _Pragma("unroll") for (int n = 0; n < 2; ++n) _Pragma("unroll") for (int k = 0; k < 2; ++k) \
;         acc[ai][bj][m][n] = __builtin_amdgcn_mfma_f32_16x16x32_bf16(Bt[n][k], At[m][k], acc[ai][bj][m][n], 0, 0, 0); __builtin_amdgcn_s_setprio(0); } while (0)
; #define PG8_WAIT_V(n) asm volatile("s_waitcnt vmcnt(" #n ")" ::: "memory")
; #define PG8_WAIT_L(n) asm volatile("s_waitcnt lgkmcnt(" #n ")" ::: "memory")
; #define PG8_BAR __builtin_amdgcn_s_barrier()
; #define PG8_SCHED __builtin_amdgcn_sched_barrier(0)
; template <class Epi>
; __device__ __forceinline__ void gemm_phase(const Lt& lt, LAS unsigned char* lds, const Gemm g, const StaticOrder& S, const Epi& E) {
;     ...
;             PG8_WAIT_V(8); PG8_WAIT_L(0); PG8_BAR; PG8_MMA(1, 0, At, B0); PG8_MMA(1, 1, At, B1); PG8_BAR; PG8_SCHED;
;             PG8_LDB(B0, 1, 0); PG8_LDB(B1, 1, 1); PG8_SCHED; PG8_LDA(At, 1, 0); PG8_STAGE(PG8_SA(0, 1), a2 + hstep, voffA);
;             PG8_WAIT_V(8); PG8_WAIT_L(0); PG8_BAR; PG8_MMA(0, 0, At, B0); PG8_MMA(0, 1, At, B1); PG8_BAR; PG8_SCHED;
;             PG8_LDA(At, 1, 1); PG8_STAGE(PG8_SB(1, 0), b3, voffB); PG8_STAGE(PG8_SB(1, 1), b3 + hstep, voffB); PG8_STAGE(PG8_SA(1, 0), a3, voffA);
	s_setprio 2
	s_waitcnt lgkmcnt(0)
	v_mfma_f32_16x16x32_bf16 v[64:67], v[144:147], v[184:187], v[64:67]
	v_mfma_f32_16x16x32_bf16 v[60:63], v[160:163], v[184:187], v[60:63]
	v_mfma_f32_16x16x32_bf16 v[56:59], v[144:147], v[192:195], v[56:59]
	v_mfma_f32_16x16x32_bf16 v[52:55], v[160:163], v[192:195], v[52:55]
	v_mfma_f32_16x16x32_bf16 v[48:51], v[144:147], v[214:217], v[48:51]
	v_mfma_f32_16x16x32_bf16 v[44:47], v[160:163], v[214:217], v[44:47]
	v_mfma_f32_16x16x32_bf16 v[40:43], v[144:147], v[222:225], v[40:43]
	v_mfma_f32_16x16x32_bf16 v[36:39], v[160:163], v[222:225], v[36:39]
	v_mfma_f32_16x16x32_bf16 v[64:67], v[156:159], v[188:191], v[64:67]
	v_mfma_f32_16x16x32_bf16 v[60:63], v[164:167], v[188:191], v[60:63]
	v_mfma_f32_16x16x32_bf16 v[56:59], v[156:159], v[210:213], v[56:59]
	v_mfma_f32_16x16x32_bf16 v[52:55], v[164:167], v[210:213], v[52:55]
	v_mfma_f32_16x16x32_bf16 v[48:51], v[156:159], v[218:221], v[48:51]
	v_mfma_f32_16x16x32_bf16 v[44:47], v[164:167], v[218:221], v[44:47]
	v_mfma_f32_16x16x32_bf16 v[40:43], v[156:159], v[226:229], v[40:43]
	v_mfma_f32_16x16x32_bf16 v[36:39], v[164:167], v[226:229], v[36:39]
	s_setprio 0
	s_setprio 2
	v_mfma_f32_16x16x32_bf16 v[32:35], v[168:171], v[184:187], v[32:35]
	v_mfma_f32_16x16x32_bf16 v[28:31], v[176:179], v[184:187], v[28:31]
	v_mfma_f32_16x16x32_bf16 v[24:27], v[168:171], v[192:195], v[24:27]
	v_mfma_f32_16x16x32_bf16 v[20:23], v[176:179], v[192:195], v[20:23]
	v_mfma_f32_16x16x32_bf16 v[16:19], v[168:171], v[214:217], v[16:19]
	v_mfma_f32_16x16x32_bf16 v[12:15], v[176:179], v[214:217], v[12:15]
	v_mfma_f32_16x16x32_bf16 v[8:11], v[168:171], v[222:225], v[8:11]
	v_mfma_f32_16x16x32_bf16 v[4:7], v[176:179], v[222:225], v[4:7]
	v_mfma_f32_16x16x32_bf16 v[32:35], v[172:175], v[188:191], v[32:35]
	v_mfma_f32_16x16x32_bf16 v[28:31], v[180:183], v[188:191], v[28:31]
	v_mfma_f32_16x16x32_bf16 v[24:27], v[172:175], v[210:213], v[24:27]
	v_mfma_f32_16x16x32_bf16 v[20:23], v[180:183], v[210:213], v[20:23]
	v_mfma_f32_16x16x32_bf16 v[16:19], v[172:175], v[218:221], v[16:19]
	v_mfma_f32_16x16x32_bf16 v[12:15], v[180:183], v[218:221], v[12:15]
	v_mfma_f32_16x16x32_bf16 v[8:11], v[172:175], v[226:229], v[8:11]
	v_mfma_f32_16x16x32_bf16 v[4:7], v[180:183], v[226:229], v[4:7]
	s_setprio 0
	s_barrier
	s_add_i32 s69, 0, 0x18000
	s_add_i32 s70, 0, 0x1c000
	v_add_u32_e32 v164, s69, v152
	v_add_u32_e32 v180, s70, v152
	ds_read_b128 v[144:147], v164
	ds_read_b128 v[156:159], v164 offset:1024
	ds_read_b128 v[160:163], v164 offset:2048
	ds_read_b128 v[164:167], v164 offset:3072
	ds_read_b128 v[168:171], v180
	ds_read_b128 v[172:175], v180 offset:1024
	ds_read_b128 v[176:179], v180 offset:2048
	ds_read_b128 v[180:183], v180 offset:3072
	s_add_u32 s50, s50, 0x80000
	s_addc_u32 s51, s51, 0
	s_mov_b32 m0, s58
	ds_read_b128 v[184:187], v155 offset:32768
	ds_read_b128 v[188:191], v155 offset:33792
	ds_read_b128 v[192:195], v155 offset:34816
	ds_read_b128 v[210:213], v155 offset:35840
	ds_read_b128 v[214:217], v155 offset:36864
	ds_read_b128 v[218:221], v155 offset:37888
	ds_read_b128 v[222:225], v155 offset:38912
	ds_read_b128 v[226:229], v155 offset:39936
	global_load_lds_dwordx4 v0, s[50:51]
	s_mov_b32 m0, s59
	s_nop 0
	global_load_lds_dwordx4 v132, s[50:51]
	s_waitcnt vmcnt(8)
	s_waitcnt lgkmcnt(0)
	s_barrier
	s_setprio 2
	s_waitcnt lgkmcnt(0)
	v_mfma_f32_16x16x32_bf16 v[128:131], v[144:147], v[184:187], v[128:131]
	v_mfma_f32_16x16x32_bf16 v[124:127], v[160:163], v[184:187], v[124:127]
	v_mfma_f32_16x16x32_bf16 v[120:123], v[144:147], v[192:195], v[120:123]
	v_mfma_f32_16x16x32_bf16 v[116:119], v[160:163], v[192:195], v[116:119]
	v_mfma_f32_16x16x32_bf16 v[112:115], v[144:147], v[214:217], v[112:115]
	v_mfma_f32_16x16x32_bf16 v[108:111], v[160:163], v[214:217], v[108:111]
	v_mfma_f32_16x16x32_bf16 v[104:107], v[144:147], v[222:225], v[104:107]
	v_mfma_f32_16x16x32_bf16 v[100:103], v[160:163], v[222:225], v[100:103]
	v_mfma_f32_16x16x32_bf16 v[128:131], v[156:159], v[188:191], v[128:131]
	v_mfma_f32_16x16x32_bf16 v[124:127], v[164:167], v[188:191], v[124:127]
	v_mfma_f32_16x16x32_bf16 v[120:123], v[156:159], v[210:213], v[120:123]
	v_mfma_f32_16x16x32_bf16 v[116:119], v[164:167], v[210:213], v[116:119]
	v_mfma_f32_16x16x32_bf16 v[112:115], v[156:159], v[218:221], v[112:115]
	v_mfma_f32_16x16x32_bf16 v[108:111], v[164:167], v[218:221], v[108:111]
	v_mfma_f32_16x16x32_bf16 v[104:107], v[156:159], v[226:229], v[104:107]
	v_mfma_f32_16x16x32_bf16 v[100:103], v[164:167], v[226:229], v[100:103]
	s_setprio 0
	s_setprio 2
	v_mfma_f32_16x16x32_bf16 v[96:99], v[168:171], v[184:187], v[96:99]
	v_mfma_f32_16x16x32_bf16 v[92:95], v[176:179], v[184:187], v[92:95]
	v_mfma_f32_16x16x32_bf16 v[88:91], v[168:171], v[192:195], v[88:91]
	v_mfma_f32_16x16x32_bf16 v[84:87], v[176:179], v[192:195], v[84:87]
	v_mfma_f32_16x16x32_bf16 v[80:83], v[168:171], v[214:217], v[80:83]
	v_mfma_f32_16x16x32_bf16 v[76:79], v[176:179], v[214:217], v[76:79]
	v_mfma_f32_16x16x32_bf16 v[72:75], v[168:171], v[222:225], v[72:75]
	v_mfma_f32_16x16x32_bf16 v[68:71], v[176:179], v[222:225], v[68:71]
	v_mfma_f32_16x16x32_bf16 v[96:99], v[172:175], v[188:191], v[96:99]
	v_mfma_f32_16x16x32_bf16 v[92:95], v[180:183], v[188:191], v[92:95]
	v_mfma_f32_16x16x32_bf16 v[88:91], v[172:175], v[210:213], v[88:91]
	v_mfma_f32_16x16x32_bf16 v[84:87], v[180:183], v[210:213], v[84:87]
	v_mfma_f32_16x16x32_bf16 v[80:83], v[172:175], v[218:221], v[80:83]
	v_mfma_f32_16x16x32_bf16 v[76:79], v[180:183], v[218:221], v[76:79]
	v_mfma_f32_16x16x32_bf16 v[72:75], v[172:175], v[226:229], v[72:75]
	v_mfma_f32_16x16x32_bf16 v[68:71], v[180:183], v[226:229], v[68:71]
	s_setprio 0
	s_barrier
; #define LAS __attribute__((address_space(3)))
; __device__ __forceinline__ unsigned cvt_pk_bf16(float lo, float hi) { const f32x2 v = {lo, hi}; return __builtin_bit_cast(unsigned, __builtin_convertvector(v, bf16x2_t)); }
; #define PG8_LDA(dst, b, h) do { _Pragma("unroll") for (int m = 0; m < 4; ++m) _Pragma("unroll") for (int k = 0; k < 2; ++k) dst[m][k] = *(const LAS bf16x8*)(lds + PG8_SA(b, h) + aoff + m * 2048 + k * 1024); } while (0)
; template <class Epi>
; __device__ __forceinline__ void gemm_phase(const Lt& lt, LAS unsigned char* lds, const Gemm g, const StaticOrder& S, const Epi& E) {
;     ...
;             PG8_LDA(At, 1, 1); PG8_STAGE(PG8_SB(1, 0), b3, voffB); PG8_STAGE(PG8_SB(1, 1), b3 + hstep, voffB); PG8_STAGE(PG8_SA(1, 0), a3, voffA);
;             PG8_WAIT_V(8); PG8_WAIT_L(0); PG8_BAR; PG8_MMA(1, 0, At, B0); PG8_MMA(1, 1, At, B1); PG8_BAR; PG8_SCHED;
;         }
;         E(acc, cur, wr, wc, fr, fq, lds, ui & 7);
;     __device__ __forceinline__ void operator()(const f32x4 (&acc)[2][2][4][2], const pg8::Unit& u, int wr, int wc, int fr, int fq, LAS unsigned char* lds, int buf) const {
;         const int row0 = u.pm * 256 + wr * 64 + fr, col0 = u.pn * 256 + wc * 32 + 8 * fq;
;         const LAS float* rst = (const LAS float*)(lds + pg8::STAGE_BYTES) + buf * 256 + wr * 64 + fr;
;         float rs[2][4];
; #pragma unroll
;         for (int ai = 0; ai < 2; ++ai)
; #pragma unroll
;             for (int m = 0; m < 4; ++m) rs[ai][m] = rst[ai * 128 + m * 16];
; #pragma unroll
;         for (int ai = 0; ai < 2; ++ai)
; #pragma unroll
;             for (int m = 0; m < 4; ++m) {
;                 const int row = row0 + ai * 128 + m * 16;
;                 bf16_t* rowp = O + (size_t)row * ldc + col0;
; #pragma unroll
;                 for (int bj = 0; bj < 2; ++bj) {
;                     f32x4 v0 = acc[ai][bj][m][0] * rs[ai][m], v1 = acc[ai][bj][m][1] * rs[ai][m];
;                     if (ACT == 1) {
; #pragma unroll
;                         for (int j = 0; j < 4; ++j) { const float a = fmaxf(v0[j], 0.f), b = fmaxf(v1[j], 0.f); v0[j] = a * a; v1[j] = b * b; }
;                     }
;                     u32x4 w; w.x = cvt_pk_bf16(v0[0], v0[1]); w.y = cvt_pk_bf16(v0[2], v0[3]); w.z = cvt_pk_bf16(v1[0], v1[1]); w.w = cvt_pk_bf16(v1[2], v1[3]);
;                     *(u32x4*)(rowp + bj * 128) = w;
;                 }
	s_add_i32 s50, s69, s57
	s_add_u32 s72, s48, s12
	s_addc_u32 s73, s49, s13
	s_mov_b32 m0, s50
	ds_read_b128 v[184:187], v155 offset:49152
	ds_read_b128 v[188:191], v155 offset:50176
	ds_read_b128 v[192:195], v155 offset:51200
	ds_read_b128 v[210:213], v155 offset:52224
	ds_read_b128 v[214:217], v155 offset:53248
	ds_read_b128 v[218:221], v155 offset:54272
	ds_read_b128 v[222:225], v155 offset:55296
	ds_read_b128 v[226:229], v155 offset:56320
	global_load_lds_dwordx4 v2, s[72:73]
	s_add_i32 m0, s50, 0x2000
	s_add_u32 s48, s48, 0x80080
	s_addc_u32 s49, s49, 0
	s_add_i32 s50, s70, s57
	global_load_lds_dwordx4 v134, s[72:73]
	s_mov_b32 m0, s50
	s_nop 0
	global_load_lds_dwordx4 v2, s[48:49]
	s_add_i32 m0, s50, 0x2000
	s_nop 0
	global_load_lds_dwordx4 v134, s[48:49]
	s_mov_b32 m0, s60
	s_nop 0
	global_load_lds_dwordx4 v0, s[78:79]
	s_mov_b32 m0, s61
	s_nop 0
	global_load_lds_dwordx4 v132, s[78:79]
	s_waitcnt vmcnt(8)
	s_waitcnt lgkmcnt(0)
	s_barrier
	s_setprio 2
	s_waitcnt lgkmcnt(0)
	v_mfma_f32_16x16x32_bf16 v[64:67], v[144:147], v[184:187], v[64:67]
	v_mfma_f32_16x16x32_bf16 v[60:63], v[160:163], v[184:187], v[60:63]
	v_mfma_f32_16x16x32_bf16 v[56:59], v[144:147], v[192:195], v[56:59]
	v_mfma_f32_16x16x32_bf16 v[52:55], v[160:163], v[192:195], v[52:55]
	v_mfma_f32_16x16x32_bf16 v[48:51], v[144:147], v[214:217], v[48:51]
	v_mfma_f32_16x16x32_bf16 v[44:47], v[160:163], v[214:217], v[44:47]
	v_mfma_f32_16x16x32_bf16 v[40:43], v[144:147], v[222:225], v[40:43]
	v_mfma_f32_16x16x32_bf16 v[36:39], v[160:163], v[222:225], v[36:39]
	v_mfma_f32_16x16x32_bf16 v[64:67], v[156:159], v[188:191], v[64:67]
	v_mfma_f32_16x16x32_bf16 v[60:63], v[164:167], v[188:191], v[60:63]
	v_mfma_f32_16x16x32_bf16 v[56:59], v[156:159], v[210:213], v[56:59]
	v_mfma_f32_16x16x32_bf16 v[52:55], v[164:167], v[210:213], v[52:55]
	v_mfma_f32_16x16x32_bf16 v[48:51], v[156:159], v[218:221], v[48:51]
	v_mfma_f32_16x16x32_bf16 v[44:47], v[164:167], v[218:221], v[44:47]
	v_mfma_f32_16x16x32_bf16 v[40:43], v[156:159], v[226:229], v[40:43]
	v_mfma_f32_16x16x32_bf16 v[36:39], v[164:167], v[226:229], v[36:39]
	s_setprio 0
	s_setprio 2
	v_mfma_f32_16x16x32_bf16 v[32:35], v[168:171], v[184:187], v[32:35]
	v_mfma_f32_16x16x32_bf16 v[28:31], v[176:179], v[184:187], v[28:31]
	v_mfma_f32_16x16x32_bf16 v[24:27], v[168:171], v[192:195], v[24:27]
	v_mfma_f32_16x16x32_bf16 v[20:23], v[176:179], v[192:195], v[20:23]
	v_mfma_f32_16x16x32_bf16 v[16:19], v[168:171], v[214:217], v[16:19]
	v_mfma_f32_16x16x32_bf16 v[12:15], v[176:179], v[214:217], v[12:15]
	v_mfma_f32_16x16x32_bf16 v[8:11], v[168:171], v[222:225], v[8:11]
	v_mfma_f32_16x16x32_bf16 v[4:7], v[176:179], v[222:225], v[4:7]
	v_mfma_f32_16x16x32_bf16 v[32:35], v[172:175], v[188:191], v[32:35]
	v_mfma_f32_16x16x32_bf16 v[28:31], v[180:183], v[188:191], v[28:31]
	v_mfma_f32_16x16x32_bf16 v[24:27], v[172:175], v[210:213], v[24:27]
	v_mfma_f32_16x16x32_bf16 v[20:23], v[180:183], v[210:213], v[20:23]
	v_mfma_f32_16x16x32_bf16 v[16:19], v[172:175], v[218:221], v[16:19]
	v_mfma_f32_16x16x32_bf16 v[12:15], v[180:183], v[218:221], v[12:15]
	v_mfma_f32_16x16x32_bf16 v[8:11], v[172:175], v[226:229], v[8:11]
	v_mfma_f32_16x16x32_bf16 v[4:7], v[180:183], v[226:229], v[4:7]
	s_setprio 0
	s_barrier
	s_add_i32 s68, s68, 2
	s_add_u32 s4, s4, 0x100
	s_addc_u32 s5, s5, 0
	s_cmp_gt_u32 s68, 29
	s_cbranch_scc0 .LBB0_78
	s_add_u32 s48, s64, 0xffffff00
	s_addc_u32 s49, s65, -1
	s_lshl_b32 s4, s62, 10
	s_and_b32 s4, s4, 0x1c00
	v_lshl_add_u32 v148, s28, 8, v151
	v_add_u32_e32 v140, s4, v153
	ds_read2_b32 v[160:161], v140 offset1:16
	ds_read2_b32 v[146:147], v140 offset0:32 offset1:48
	ds_read2_b32 v[144:145], v140 offset0:128 offset1:144
	ds_read2_b32 v[142:143], v140 offset0:160 offset1:176
	v_lshl_or_b32 v140, s30, 8, v154
	v_ashrrev_i32_e32 v149, 31, v148
	v_ashrrev_i32_e32 v141, 31, v140
	v_lshlrev_b64 v[156:157], 14, v[148:149]
	v_lshl_add_u64 v[156:157], s[34:35], 0, v[156:157]
	v_lshlrev_b64 v[162:163], 1, v[140:141]
	v_lshl_add_u64 v[140:141], v[156:157], 0, v[162:163]
	s_waitcnt lgkmcnt(0)
	v_pk_mul_f32 v[156:157], v[130:131], v[160:161] op_sel_hi:[1,0]
	v_pk_mul_f32 v[158:159], v[128:129], v[160:161] op_sel_hi:[1,0]
	v_pk_mul_f32 v[164:165], v[126:127], v[160:161] op_sel_hi:[1,0]
	v_pk_mul_f32 v[166:167], v[124:125], v[160:161] op_sel_hi:[1,0]
	v_max_f32_e32 v158, 0, v158
	v_max_f32_e32 v166, 0, v166
	v_max_f32_e32 v159, 0, v159
	v_max_f32_e32 v167, 0, v167
	v_max_f32_e32 v156, 0, v156
	v_max_f32_e32 v164, 0, v164
	v_max_f32_e32 v157, 0, v157
	v_max_f32_e32 v165, 0, v165
	v_pk_mul_f32 v[158:159], v[158:159], v[158:159]
	v_pk_mul_f32 v[166:167], v[166:167], v[166:167]
	v_pk_mul_f32 v[168:169], v[156:157], v[156:157]
	v_pk_mul_f32 v[164:165], v[164:165], v[164:165]
	v_cvt_pk_bf16_f32 v156, v158, v159
	v_cvt_pk_bf16_f32 v157, v168, v169
	v_cvt_pk_bf16_f32 v158, v166, v167
	v_cvt_pk_bf16_f32 v159, v164, v165
	global_store_dwordx4 v[140:141], v[156:159], off
	v_pk_mul_f32 v[164:165], v[94:95], v[160:161] op_sel_hi:[1,0]
	v_pk_mul_f32 v[166:167], v[92:93], v[160:161] op_sel_hi:[1,0]
	v_pk_mul_f32 v[156:157], v[98:99], v[160:161] op_sel_hi:[1,0]
	v_pk_mul_f32 v[158:159], v[96:97], v[160:161] op_sel_hi:[1,0]
	v_max_f32_e32 v166, 0, v166
	v_max_f32_e32 v158, 0, v158
	v_max_f32_e32 v159, 0, v159
	v_max_f32_e32 v167, 0, v167
	v_max_f32_e32 v156, 0, v156
	v_max_f32_e32 v164, 0, v164
	v_max_f32_e32 v157, 0, v157
	v_max_f32_e32 v165, 0, v165
	v_pk_mul_f32 v[158:159], v[158:159], v[158:159]
	v_pk_mul_f32 v[166:167], v[166:167], v[166:167]
	v_pk_mul_f32 v[168:169], v[156:157], v[156:157]
	v_pk_mul_f32 v[164:165], v[164:165], v[164:165]
	v_cvt_pk_bf16_f32 v156, v158, v159
; __device__ __forceinline__ unsigned cvt_pk_bf16(float lo, float hi) { const f32x2 v = {lo, hi}; return __builtin_bit_cast(unsigned, __builtin_convertvector(v, bf16x2_t)); }
;     __device__ __forceinline__ void operator()(const f32x4 (&acc)[2][2][4][2], const pg8::Unit& u, int wr, int wc, int fr, int fq, LAS unsigned char* lds, int buf) const {
;     ...
; #pragma unroll
;         for (int ai = 0; ai < 2; ++ai)
; #pragma unroll
;             for (int m = 0; m < 4; ++m) {
;                 const int row = row0 + ai * 128 + m * 16;
;                 bf16_t* rowp = O + (size_t)row * ldc + col0;
; #pragma unroll
;                 for (int bj = 0; bj < 2; ++bj) {
;                     f32x4 v0 = acc[ai][bj][m][0] * rs[ai][m], v1 = acc[ai][bj][m][1] * rs[ai][m];
;                     if (ACT == 1) {
; #pragma unroll
;                         for (int j = 0; j < 4; ++j) { const float a = fmaxf(v0[j], 0.f), b = fmaxf(v1[j], 0.f); v0[j] = a * a; v1[j] = b * b; }
;                     }
;                     u32x4 w; w.x = cvt_pk_bf16(v0[0], v0[1]); w.y = cvt_pk_bf16(v0[2], v0[3]); w.z = cvt_pk_bf16(v1[0], v1[1]); w.w = cvt_pk_bf16(v1[2], v1[3]);
;                     *(u32x4*)(rowp + bj * 128) = w;
;                 }
	v_cvt_pk_bf16_f32 v157, v168, v169
	v_cvt_pk_bf16_f32 v158, v166, v167
	v_cvt_pk_bf16_f32 v159, v164, v165
	global_store_dwordx4 v[140:141], v[156:159], off offset:256
	v_mov_b32_e32 v160, v161
	v_pk_mul_f32 v[166:167], v[118:119], v[160:161] op_sel_hi:[1,0]
	v_or_b32_e32 v156, 16, v148
	v_ashrrev_i32_e32 v157, 31, v156
	v_lshlrev_b64 v[156:157], 14, v[156:157]
	v_lshl_add_u64 v[156:157], s[34:35], 0, v[156:157]
	v_lshl_add_u64 v[164:165], v[156:157], 0, v[162:163]
	v_pk_mul_f32 v[156:157], v[122:123], v[160:161] op_sel_hi:[1,0]
	v_pk_mul_f32 v[158:159], v[120:121], v[160:161] op_sel_hi:[1,0]
	v_pk_mul_f32 v[168:169], v[116:117], v[160:161] op_sel_hi:[1,0]
	v_max_f32_e32 v158, 0, v158
	v_max_f32_e32 v168, 0, v168
	v_max_f32_e32 v159, 0, v159
	v_max_f32_e32 v169, 0, v169
	v_max_f32_e32 v156, 0, v156
	v_max_f32_e32 v166, 0, v166
	v_max_f32_e32 v157, 0, v157
	v_max_f32_e32 v167, 0, v167
	v_pk_mul_f32 v[158:159], v[158:159], v[158:159]
	v_pk_mul_f32 v[168:169], v[168:169], v[168:169]
	v_pk_mul_f32 v[170:171], v[156:157], v[156:157]
	v_pk_mul_f32 v[166:167], v[166:167], v[166:167]
	v_cvt_pk_bf16_f32 v156, v158, v159
	v_cvt_pk_bf16_f32 v157, v170, v171
	v_cvt_pk_bf16_f32 v158, v168, v169
	v_cvt_pk_bf16_f32 v159, v166, v167
	global_store_dwordx4 v[164:165], v[156:159], off
	v_pk_mul_f32 v[166:167], v[86:87], v[160:161] op_sel_hi:[1,0]
	s_mov_b64 s[4:5], 0x200000
	v_pk_mul_f32 v[156:157], v[90:91], v[160:161] op_sel_hi:[1,0]
	v_pk_mul_f32 v[158:159], v[88:89], v[160:161] op_sel_hi:[1,0]
	v_pk_mul_f32 v[160:161], v[84:85], v[160:161] op_sel_hi:[1,0]
	v_max_f32_e32 v158, 0, v158
	v_max_f32_e32 v160, 0, v160
	v_max_f32_e32 v159, 0, v159
	v_max_f32_e32 v161, 0, v161
	v_max_f32_e32 v156, 0, v156
	v_max_f32_e32 v166, 0, v166
	v_max_f32_e32 v157, 0, v157
	v_max_f32_e32 v167, 0, v167
	v_pk_mul_f32 v[158:159], v[158:159], v[158:159]
	v_pk_mul_f32 v[160:161], v[160:161], v[160:161]
	v_pk_mul_f32 v[168:169], v[156:157], v[156:157]
	v_pk_mul_f32 v[166:167], v[166:167], v[166:167]
	v_cvt_pk_bf16_f32 v156, v158, v159
	v_cvt_pk_bf16_f32 v157, v168, v169
	v_cvt_pk_bf16_f32 v158, v160, v161
	v_cvt_pk_bf16_f32 v159, v166, v167
	global_store_dwordx4 v[164:165], v[156:159], off offset:256
	v_pk_mul_f32 v[164:165], v[110:111], v[146:147] op_sel_hi:[1,0]
	v_pk_mul_f32 v[166:167], v[108:109], v[146:147] op_sel_hi:[1,0]
	v_or_b32_e32 v156, 32, v148
	v_ashrrev_i32_e32 v157, 31, v156
	v_lshlrev_b64 v[156:157], 14, v[156:157]
	v_lshl_add_u64 v[156:157], s[34:35], 0, v[156:157]
	v_lshl_add_u64 v[160:161], v[156:157], 0, v[162:163]
	v_pk_mul_f32 v[156:157], v[114:115], v[146:147] op_sel_hi:[1,0]
	v_pk_mul_f32 v[158:159], v[112:113], v[146:147] op_sel_hi:[1,0]
	v_max_f32_e32 v166, 0, v166
	v_max_f32_e32 v158, 0, v158
	v_max_f32_e32 v159, 0, v159
	v_max_f32_e32 v167, 0, v167
	v_max_f32_e32 v156, 0, v156
	v_max_f32_e32 v164, 0, v164
	v_max_f32_e32 v157, 0, v157
	v_max_f32_e32 v165, 0, v165
	v_pk_mul_f32 v[158:159], v[158:159], v[158:159]
	v_pk_mul_f32 v[166:167], v[166:167], v[166:167]
	v_pk_mul_f32 v[168:169], v[156:157], v[156:157]
	v_pk_mul_f32 v[164:165], v[164:165], v[164:165]
	v_cvt_pk_bf16_f32 v156, v158, v159
	v_cvt_pk_bf16_f32 v157, v168, v169
	v_cvt_pk_bf16_f32 v158, v166, v167
	v_cvt_pk_bf16_f32 v159, v164, v165
	global_store_dwordx4 v[160:161], v[156:159], off
	v_pk_mul_f32 v[164:165], v[78:79], v[146:147] op_sel_hi:[1,0]
	v_pk_mul_f32 v[166:167], v[76:77], v[146:147] op_sel_hi:[1,0]
	v_pk_mul_f32 v[156:157], v[82:83], v[146:147] op_sel_hi:[1,0]
	v_pk_mul_f32 v[158:159], v[80:81], v[146:147] op_sel_hi:[1,0]
	v_max_f32_e32 v166, 0, v166
	v_max_f32_e32 v158, 0, v158
	v_max_f32_e32 v159, 0, v159
	v_max_f32_e32 v167, 0, v167
	v_max_f32_e32 v156, 0, v156
	v_max_f32_e32 v164, 0, v164
	v_max_f32_e32 v157, 0, v157
	v_max_f32_e32 v165, 0, v165
	v_or_b32_e32 v148, 48, v148
	v_pk_mul_f32 v[158:159], v[158:159], v[158:159]
	v_pk_mul_f32 v[166:167], v[166:167], v[166:167]
	v_pk_mul_f32 v[168:169], v[156:157], v[156:157]
	v_pk_mul_f32 v[164:165], v[164:165], v[164:165]
	v_ashrrev_i32_e32 v149, 31, v148
	v_cvt_pk_bf16_f32 v156, v158, v159
	v_cvt_pk_bf16_f32 v157, v168, v169
	v_cvt_pk_bf16_f32 v158, v166, v167
	v_cvt_pk_bf16_f32 v159, v164, v165
	v_lshlrev_b64 v[148:149], 14, v[148:149]
	global_store_dwordx4 v[160:161], v[156:159], off offset:256
	v_lshl_add_u64 v[148:149], s[34:35], 0, v[148:149]
	s_and_b64 vcc, vcc, exec
	v_mov_b32_e32 v158, v147
	v_lshl_add_u64 v[156:157], v[148:149], 0, v[162:163]
	v_pk_mul_f32 v[146:147], v[106:107], v[158:159] op_sel_hi:[1,0]
	v_pk_mul_f32 v[148:149], v[104:105], v[158:159] op_sel_hi:[1,0]
	v_pk_mul_f32 v[160:161], v[102:103], v[158:159] op_sel_hi:[1,0]
	v_pk_mul_f32 v[162:163], v[100:101], v[158:159] op_sel_hi:[1,0]
	v_max_f32_e32 v148, 0, v148
	v_max_f32_e32 v162, 0, v162
	v_max_f32_e32 v149, 0, v149
	v_max_f32_e32 v163, 0, v163
	v_max_f32_e32 v146, 0, v146
	v_max_f32_e32 v160, 0, v160
	v_max_f32_e32 v147, 0, v147
	v_max_f32_e32 v161, 0, v161
	v_pk_mul_f32 v[148:149], v[148:149], v[148:149]
	v_pk_mul_f32 v[162:163], v[162:163], v[162:163]
	v_pk_mul_f32 v[164:165], v[146:147], v[146:147]
	v_pk_mul_f32 v[160:161], v[160:161], v[160:161]
	v_cvt_pk_bf16_f32 v146, v148, v149
	v_cvt_pk_bf16_f32 v147, v164, v165
	v_cvt_pk_bf16_f32 v148, v162, v163
	v_cvt_pk_bf16_f32 v149, v160, v161
	global_store_dwordx4 v[156:157], v[146:149], off
	v_pk_mul_f32 v[160:161], v[70:71], v[158:159] op_sel_hi:[1,0]
	s_nop 0
	v_pk_mul_f32 v[146:147], v[74:75], v[158:159] op_sel_hi:[1,0]
	v_pk_mul_f32 v[148:149], v[72:73], v[158:159] op_sel_hi:[1,0]
	v_pk_mul_f32 v[158:159], v[68:69], v[158:159] op_sel_hi:[1,0]
	v_max_f32_e32 v148, 0, v148
	v_max_f32_e32 v158, 0, v158
; __device__ __forceinline__ unsigned cvt_pk_bf16(float lo, float hi) { const f32x2 v = {lo, hi}; return __builtin_bit_cast(unsigned, __builtin_convertvector(v, bf16x2_t)); }
;     __device__ __forceinline__ void operator()(const f32x4 (&acc)[2][2][4][2], const pg8::Unit& u, int wr, int wc, int fr, int fq, LAS unsigned char* lds, int buf) const {
;     ...
; #pragma unroll
;         for (int ai = 0; ai < 2; ++ai)
; #pragma unroll
;             for (int m = 0; m < 4; ++m) {
;                 const int row = row0 + ai * 128 + m * 16;
;                 bf16_t* rowp = O + (size_t)row * ldc + col0;
; #pragma unroll
;                 for (int bj = 0; bj < 2; ++bj) {
;                     f32x4 v0 = acc[ai][bj][m][0] * rs[ai][m], v1 = acc[ai][bj][m][1] * rs[ai][m];
;                     if (ACT == 1) {
; #pragma unroll
;                         for (int j = 0; j < 4; ++j) { const float a = fmaxf(v0[j], 0.f), b = fmaxf(v1[j], 0.f); v0[j] = a * a; v1[j] = b * b; }
;                     }
;                     u32x4 w; w.x = cvt_pk_bf16(v0[0], v0[1]); w.y = cvt_pk_bf16(v0[2], v0[3]); w.z = cvt_pk_bf16(v1[0], v1[1]); w.w = cvt_pk_bf16(v1[2], v1[3]);
;                     *(u32x4*)(rowp + bj * 128) = w;
;                 }
	v_max_f32_e32 v149, 0, v149
	v_max_f32_e32 v159, 0, v159
	v_max_f32_e32 v146, 0, v146
	v_max_f32_e32 v160, 0, v160
	v_max_f32_e32 v147, 0, v147
	v_max_f32_e32 v161, 0, v161
	v_pk_mul_f32 v[148:149], v[148:149], v[148:149]
	v_pk_mul_f32 v[158:159], v[158:159], v[158:159]
	v_pk_mul_f32 v[162:163], v[146:147], v[146:147]
	v_pk_mul_f32 v[160:161], v[160:161], v[160:161]
	v_cvt_pk_bf16_f32 v146, v148, v149
	v_cvt_pk_bf16_f32 v147, v162, v163
	v_cvt_pk_bf16_f32 v148, v158, v159
	v_cvt_pk_bf16_f32 v149, v160, v161
	global_store_dwordx4 v[156:157], v[146:149], off offset:256
	v_pk_mul_f32 v[158:159], v[62:63], v[144:145] op_sel_hi:[1,0]
	v_pk_mul_f32 v[160:161], v[60:61], v[144:145] op_sel_hi:[1,0]
	v_pk_mul_f32 v[148:149], v[64:65], v[144:145] op_sel_hi:[1,0]
	v_pk_mul_f32 v[146:147], v[66:67], v[144:145] op_sel_hi:[1,0]
	v_max_f32_e32 v148, 0, v148
	v_max_f32_e32 v149, 0, v149
	v_max_f32_e32 v158, 0, v158
	v_max_f32_e32 v159, 0, v159
	v_lshl_add_u64 v[156:157], v[140:141], 0, s[4:5]
	v_max_f32_e32 v160, 0, v160
	v_max_f32_e32 v161, 0, v161
	v_pk_mul_f32 v[148:149], v[148:149], v[148:149]
	v_max_f32_e32 v146, 0, v146
	v_max_f32_e32 v147, 0, v147
	v_pk_mul_f32 v[158:159], v[158:159], v[158:159]
	s_mov_b32 s4, 0x200000
	v_pk_mul_f32 v[160:161], v[160:161], v[160:161]
	v_pk_mul_f32 v[162:163], v[146:147], v[146:147]
	v_cvt_pk_bf16_f32 v146, v148, v149
	v_cvt_pk_bf16_f32 v149, v158, v159
	v_add_co_u32_e64 v158, s[4:5], s4, v140
	v_cvt_pk_bf16_f32 v147, v162, v163
	v_cvt_pk_bf16_f32 v148, v160, v161
	v_addc_co_u32_e64 v159, s[4:5], 0, v141, s[4:5]
	global_store_dwordx4 v[158:159], v[146:149], off
	v_pk_mul_f32 v[158:159], v[30:31], v[144:145] op_sel_hi:[1,0]
	v_pk_mul_f32 v[160:161], v[28:29], v[144:145] op_sel_hi:[1,0]
	v_pk_mul_f32 v[146:147], v[34:35], v[144:145] op_sel_hi:[1,0]
	v_pk_mul_f32 v[148:149], v[32:33], v[144:145] op_sel_hi:[1,0]
	v_max_f32_e32 v160, 0, v160
	v_max_f32_e32 v148, 0, v148
	v_max_f32_e32 v149, 0, v149
	v_max_f32_e32 v161, 0, v161
	v_max_f32_e32 v146, 0, v146
	v_max_f32_e32 v158, 0, v158
	v_max_f32_e32 v147, 0, v147
	v_max_f32_e32 v159, 0, v159
	v_pk_mul_f32 v[148:149], v[148:149], v[148:149]
	v_pk_mul_f32 v[160:161], v[160:161], v[160:161]
	v_pk_mul_f32 v[162:163], v[146:147], v[146:147]
	v_pk_mul_f32 v[158:159], v[158:159], v[158:159]
	v_cvt_pk_bf16_f32 v146, v148, v149
	v_cvt_pk_bf16_f32 v147, v162, v163
	v_cvt_pk_bf16_f32 v148, v160, v161
	v_cvt_pk_bf16_f32 v149, v158, v159
	global_store_dwordx4 v[156:157], v[146:149], off offset:256
	v_mov_b32_e32 v156, v145
	v_pk_mul_f32 v[158:159], v[54:55], v[156:157] op_sel_hi:[1,0]
	v_pk_mul_f32 v[146:147], v[56:57], v[156:157] op_sel_hi:[1,0]
	s_mov_b64 s[4:5], 0x240000
	v_pk_mul_f32 v[144:145], v[58:59], v[156:157] op_sel_hi:[1,0]
	v_pk_mul_f32 v[160:161], v[52:53], v[156:157] op_sel_hi:[1,0]
	v_max_f32_e32 v146, 0, v146
	v_max_f32_e32 v147, 0, v147
	v_max_f32_e32 v158, 0, v158
	v_max_f32_e32 v159, 0, v159
	v_lshl_add_u64 v[148:149], v[140:141], 0, s[4:5]
	v_max_f32_e32 v160, 0, v160
	v_max_f32_e32 v161, 0, v161
	v_pk_mul_f32 v[146:147], v[146:147], v[146:147]
	v_max_f32_e32 v144, 0, v144
	v_max_f32_e32 v145, 0, v145
	v_pk_mul_f32 v[158:159], v[158:159], v[158:159]
	s_mov_b32 s4, 0x240000
	v_pk_mul_f32 v[160:161], v[160:161], v[160:161]
	v_pk_mul_f32 v[162:163], v[144:145], v[144:145]
	v_cvt_pk_bf16_f32 v144, v146, v147
	v_cvt_pk_bf16_f32 v147, v158, v159
	v_add_co_u32_e64 v158, s[4:5], s4, v140
	v_cvt_pk_bf16_f32 v145, v162, v163
	v_cvt_pk_bf16_f32 v146, v160, v161
	v_addc_co_u32_e64 v159, s[4:5], 0, v141, s[4:5]
	global_store_dwordx4 v[158:159], v[144:147], off
	v_pk_mul_f32 v[158:159], v[22:23], v[156:157] op_sel_hi:[1,0]
	s_mov_b64 s[4:5], 0x280000
	v_pk_mul_f32 v[144:145], v[26:27], v[156:157] op_sel_hi:[1,0]
	v_pk_mul_f32 v[146:147], v[24:25], v[156:157] op_sel_hi:[1,0]
	v_pk_mul_f32 v[156:157], v[20:21], v[156:157] op_sel_hi:[1,0]
	v_max_f32_e32 v146, 0, v146
	v_max_f32_e32 v156, 0, v156
	v_max_f32_e32 v147, 0, v147
	v_max_f32_e32 v157, 0, v157
	v_max_f32_e32 v144, 0, v144
	v_max_f32_e32 v158, 0, v158
	v_max_f32_e32 v145, 0, v145
	v_max_f32_e32 v159, 0, v159
	v_pk_mul_f32 v[146:147], v[146:147], v[146:147]
	v_pk_mul_f32 v[156:157], v[156:157], v[156:157]
	v_pk_mul_f32 v[160:161], v[144:145], v[144:145]
	v_pk_mul_f32 v[158:159], v[158:159], v[158:159]
	v_cvt_pk_bf16_f32 v144, v146, v147
	v_cvt_pk_bf16_f32 v145, v160, v161
	v_cvt_pk_bf16_f32 v146, v156, v157
	v_cvt_pk_bf16_f32 v147, v158, v159
	global_store_dwordx4 v[148:149], v[144:147], off offset:256
	v_pk_mul_f32 v[156:157], v[46:47], v[142:143] op_sel_hi:[1,0]
	v_pk_mul_f32 v[158:159], v[44:45], v[142:143] op_sel_hi:[1,0]
	v_pk_mul_f32 v[146:147], v[48:49], v[142:143] op_sel_hi:[1,0]
	v_pk_mul_f32 v[144:145], v[50:51], v[142:143] op_sel_hi:[1,0]
	v_max_f32_e32 v146, 0, v146
	v_max_f32_e32 v147, 0, v147
	v_max_f32_e32 v156, 0, v156
	v_max_f32_e32 v157, 0, v157
	v_lshl_add_u64 v[148:149], v[140:141], 0, s[4:5]
	v_max_f32_e32 v158, 0, v158
	v_max_f32_e32 v159, 0, v159
	v_pk_mul_f32 v[146:147], v[146:147], v[146:147]
	v_max_f32_e32 v144, 0, v144
	v_max_f32_e32 v145, 0, v145
	v_pk_mul_f32 v[156:157], v[156:157], v[156:157]
; __device__ __forceinline__ unsigned cvt_pk_bf16(float lo, float hi) { const f32x2 v = {lo, hi}; return __builtin_bit_cast(unsigned, __builtin_convertvector(v, bf16x2_t)); }
; __device__ __forceinline__ float row_rstd(const float* ssq, int row, float inv_n) {
;     const f32x4* p = (const f32x4*)(ssq + (size_t)row * 32);
;     f32x4 s = p[0];
; #pragma unroll
;     for (int i = 1; i < 8; ++i) s += p[i];
;     return rsqrtf((s[0] + s[1] + s[2] + s[3]) * inv_n + NORM_EPS);
; }
;     __device__ __forceinline__ void operator()(const f32x4 (&acc)[2][2][4][2], const pg8::Unit& u, int wr, int wc, int fr, int fq, LAS unsigned char* lds, int buf) const {
;     ...
;             for (int m = 0; m < 4; ++m) {
;                 const int row = row0 + ai * 128 + m * 16;
;                 bf16_t* rowp = O + (size_t)row * ldc + col0;
; #pragma unroll
;                 for (int bj = 0; bj < 2; ++bj) {
;                     f32x4 v0 = acc[ai][bj][m][0] * rs[ai][m], v1 = acc[ai][bj][m][1] * rs[ai][m];
;                     if (ACT == 1) {
; #pragma unroll
;                         for (int j = 0; j < 4; ++j) { const float a = fmaxf(v0[j], 0.f), b = fmaxf(v1[j], 0.f); v0[j] = a * a; v1[j] = b * b; }
;                     }
;                     u32x4 w; w.x = cvt_pk_bf16(v0[0], v0[1]); w.y = cvt_pk_bf16(v0[2], v0[3]); w.z = cvt_pk_bf16(v1[0], v1[1]); w.w = cvt_pk_bf16(v1[2], v1[3]);
;                     *(u32x4*)(rowp + bj * 128) = w;
;                 }
	s_mov_b32 s4, 0x280000
	v_pk_mul_f32 v[158:159], v[158:159], v[158:159]
	v_pk_mul_f32 v[160:161], v[144:145], v[144:145]
	v_cvt_pk_bf16_f32 v144, v146, v147
	v_cvt_pk_bf16_f32 v147, v156, v157
	v_add_co_u32_e64 v156, s[4:5], s4, v140
	v_cvt_pk_bf16_f32 v145, v160, v161
	v_cvt_pk_bf16_f32 v146, v158, v159
	v_addc_co_u32_e64 v157, s[4:5], 0, v141, s[4:5]
	global_store_dwordx4 v[156:157], v[144:147], off
	v_pk_mul_f32 v[156:157], v[14:15], v[142:143] op_sel_hi:[1,0]
	v_pk_mul_f32 v[158:159], v[12:13], v[142:143] op_sel_hi:[1,0]
	v_pk_mul_f32 v[144:145], v[18:19], v[142:143] op_sel_hi:[1,0]
	v_pk_mul_f32 v[146:147], v[16:17], v[142:143] op_sel_hi:[1,0]
	v_max_f32_e32 v158, 0, v158
	v_max_f32_e32 v146, 0, v146
	v_max_f32_e32 v147, 0, v147
	v_max_f32_e32 v159, 0, v159
	v_max_f32_e32 v144, 0, v144
	v_max_f32_e32 v156, 0, v156
	v_max_f32_e32 v145, 0, v145
	v_max_f32_e32 v157, 0, v157
	v_pk_mul_f32 v[146:147], v[146:147], v[146:147]
	v_pk_mul_f32 v[158:159], v[158:159], v[158:159]
	v_pk_mul_f32 v[160:161], v[144:145], v[144:145]
	v_pk_mul_f32 v[156:157], v[156:157], v[156:157]
	v_cvt_pk_bf16_f32 v144, v146, v147
	v_cvt_pk_bf16_f32 v145, v160, v161
	v_cvt_pk_bf16_f32 v146, v158, v159
	v_cvt_pk_bf16_f32 v147, v156, v157
	global_store_dwordx4 v[148:149], v[144:147], off offset:256
	v_mov_b32_e32 v148, v143
	s_mov_b64 s[4:5], 0x2c0000
	v_pk_mul_f32 v[142:143], v[42:43], v[148:149] op_sel_hi:[1,0]
	v_pk_mul_f32 v[144:145], v[40:41], v[148:149] op_sel_hi:[1,0]
	v_pk_mul_f32 v[156:157], v[38:39], v[148:149] op_sel_hi:[1,0]
	v_pk_mul_f32 v[158:159], v[36:37], v[148:149] op_sel_hi:[1,0]
	v_lshl_add_u64 v[146:147], v[140:141], 0, s[4:5]
	v_max_f32_e32 v144, 0, v144
	v_max_f32_e32 v158, 0, v158
	v_max_f32_e32 v145, 0, v145
	v_max_f32_e32 v159, 0, v159
	v_max_f32_e32 v142, 0, v142
	v_max_f32_e32 v156, 0, v156
	v_max_f32_e32 v143, 0, v143
	v_max_f32_e32 v157, 0, v157
	s_mov_b32 s4, 0x2c0000
	v_pk_mul_f32 v[144:145], v[144:145], v[144:145]
	v_pk_mul_f32 v[158:159], v[158:159], v[158:159]
	v_pk_mul_f32 v[160:161], v[142:143], v[142:143]
	v_pk_mul_f32 v[156:157], v[156:157], v[156:157]
	v_add_co_u32_e64 v140, s[4:5], s4, v140
	v_cvt_pk_bf16_f32 v142, v144, v145
	v_cvt_pk_bf16_f32 v143, v160, v161
	v_cvt_pk_bf16_f32 v144, v158, v159
	v_cvt_pk_bf16_f32 v145, v156, v157
	v_addc_co_u32_e64 v141, s[4:5], 0, v141, s[4:5]
	global_store_dwordx4 v[140:141], v[142:145], off
	v_pk_mul_f32 v[140:141], v[10:11], v[148:149] op_sel_hi:[1,0]
	s_nop 0
	v_pk_mul_f32 v[142:143], v[8:9], v[148:149] op_sel_hi:[1,0]
	v_pk_mul_f32 v[144:145], v[6:7], v[148:149] op_sel_hi:[1,0]
	v_pk_mul_f32 v[148:149], v[4:5], v[148:149] op_sel_hi:[1,0]
	v_max_f32_e32 v142, 0, v142
	v_max_f32_e32 v148, 0, v148
	v_max_f32_e32 v143, 0, v143
	v_max_f32_e32 v149, 0, v149
	v_max_f32_e32 v140, 0, v140
	v_max_f32_e32 v144, 0, v144
	v_max_f32_e32 v141, 0, v141
	v_max_f32_e32 v145, 0, v145
	v_pk_mul_f32 v[142:143], v[142:143], v[142:143]
	v_pk_mul_f32 v[148:149], v[148:149], v[148:149]
	v_pk_mul_f32 v[156:157], v[140:141], v[140:141]
	v_pk_mul_f32 v[144:145], v[144:145], v[144:145]
	v_cvt_pk_bf16_f32 v140, v142, v143
	v_cvt_pk_bf16_f32 v141, v156, v157
	v_cvt_pk_bf16_f32 v142, v148, v149
	v_cvt_pk_bf16_f32 v143, v144, v145
	global_store_dwordx4 v[146:147], v[140:143], off offset:256
	s_cbranch_vccz .LBB0_82
	s_cmp_gt_i32 s62, 6
	s_cselect_b64 s[4:5], -1, 0
	s_and_b64 s[42:43], s[4:5], s[38:39]
	s_and_saveexec_b64 s[4:5], s[42:43]
	s_movk_i32 s71, 0x2000
	s_cbranch_execz .LBB0_70
	v_lshl_add_u32 v4, s40, 8, v245
	v_ashrrev_i32_e32 v5, 31, v4
	v_lshlrev_b64 v[4:5], 7, v[4:5]
	v_lshl_add_u64 v[20:21], s[8:9], 0, v[4:5]
	global_load_dwordx4 v[4:7], v[20:21], off offset:48
	global_load_dwordx4 v[8:11], v[20:21], off offset:32
	global_load_dwordx4 v[12:15], v[20:21], off
	global_load_dwordx4 v[16:19], v[20:21], off offset:16
	s_lshl_b32 s28, s63, 10
	s_and_b32 s28, s28, 0x1c00
	s_waitcnt vmcnt(0)
	v_pk_add_f32 v[14:15], v[14:15], v[18:19]
	v_pk_add_f32 v[12:13], v[12:13], v[16:17]
	v_pk_add_f32 v[10:11], v[14:15], v[10:11]
	v_pk_add_f32 v[8:9], v[12:13], v[8:9]
	v_pk_add_f32 v[22:23], v[10:11], v[6:7]
	v_pk_add_f32 v[24:25], v[8:9], v[4:5]
	global_load_dwordx4 v[4:7], v[20:21], off offset:112
	global_load_dwordx4 v[8:11], v[20:21], off offset:96
	global_load_dwordx4 v[12:15], v[20:21], off offset:80
	global_load_dwordx4 v[16:19], v[20:21], off offset:64
	s_waitcnt vmcnt(0)
	v_pk_add_f32 v[16:17], v[24:25], v[16:17]
	v_pk_add_f32 v[18:19], v[22:23], v[18:19]
	v_pk_add_f32 v[12:13], v[16:17], v[12:13]
	v_pk_add_f32 v[14:15], v[18:19], v[14:15]
	v_pk_add_f32 v[8:9], v[12:13], v[8:9]
	v_pk_add_f32 v[10:11], v[14:15], v[10:11]
	v_pk_add_f32 v[4:5], v[8:9], v[4:5]
	v_pk_add_f32 v[6:7], v[10:11], v[6:7]
	v_add_f32_e32 v4, v4, v5
	v_add_f32_e32 v4, v6, v4
	v_add_f32_e32 v4, v7, v4
	v_fmamk_f32 v4, v4, 0x3a000000, v197
	v_cmp_gt_f32_e32 vcc, s75, v4
	v_mul_f32_e32 v5, 0x4b800000, v4
	s_nop 0
	v_cndmask_b32_e32 v4, v4, v5, vcc
	v_rsq_f32_e32 v4, v4
	s_nop 0
	v_mul_f32_e32 v5, 0x45800000, v4
	v_cndmask_b32_e32 v4, v4, v5, vcc
	v_add_u32_e32 v5, s28, v150
	ds_write_b32 v5, v4
	s_branch .LBB0_70

; #define PG8_STAGE(bufoff, gbase, voff) do { _Pragma("unroll") for (int _i = 0; _i < 2; ++_i) \
;         __builtin_amdgcn_global_load_lds((const unsigned*)((const char*)(gbase) + (voff)[_i]), (LAS unsigned*)(lds + (bufoff) + ldsw + _i * 8192), 16, 0, 0); } while (0)
; #define PG8_LDA(dst, b, h) do { _Pragma("unroll") for (int m = 0; m < 4; ++m) _Pragma("unroll") for (int k = 0; k < 2; ++k) dst[m][k] = *(const LAS bf16x8*)(lds + PG8_SA(b, h) + aoff + m * 2048 + k * 1024); } while (0)
; #define PG8_LDB(dst, b, h) do { _Pragma("unroll") for (int n = 0; n < 2; ++n) _Pragma("unroll") for (int k = 0; k < 2; ++k) dst[n][k] = *(const LAS bf16x8*)(lds + PG8_SB(b, h) + boff + n * 2048 + k * 1024); } while (0)
; #define PG8_MMA(ai, bj, At, Bt) do { __builtin_amdgcn_s_setprio(2); _Pragma("unroll") for (int m = 0; m < 4; ++m) _Pragma("unroll") for (int n = 0; n < 2; ++n) _Pragma("unroll") for (int k = 0; k < 2; ++k) \
;         acc[ai][bj][m][n] = __builtin_amdgcn_mfma_f32_16x16x32_bf16(Bt[n][k], At[m][k], acc[ai][bj][m][n], 0, 0, 0); __builtin_amdgcn_s_setprio(0); } while (0)
; #define PG8_WAIT_V(n) asm volatile("s_waitcnt vmcnt(" #n ")" ::: "memory")
; #define PG8_WAIT_L(n) asm volatile("s_waitcnt lgkmcnt(" #n ")" ::: "memory")
; #define PG8_BAR __builtin_amdgcn_s_barrier()
; #define PG8_SCHED __builtin_amdgcn_sched_barrier(0)
; template <class Epi>
; __device__ __forceinline__ void gemm_phase(const Lt& lt, LAS unsigned char* lds, const Gemm g, const StaticOrder& S, const Epi& E) {
;     ...
;             const char* a1 = cA + (size_t)(t + 1) * kstep;
;             const char* a2 = last ? nA : cA + (size_t)(t + 2) * kstep; const char* b2 = last ? nB : cB + (size_t)(t + 2) * kstep;
;             const char* a3 = a2 + kstep; const char* b3 = b2 + kstep;
;             PG8_LDB(B0, 0, 0); PG8_LDB(B1, 0, 1); PG8_SCHED; PG8_LDA(At, 0, 0); PG8_STAGE(PG8_SA(1, 1), a1 + hstep, voffA);
;             PG8_WAIT_V(8); PG8_WAIT_L(0); PG8_BAR; PG8_MMA(0, 0, At, B0); PG8_MMA(0, 1, At, B1); PG8_BAR; PG8_SCHED;
;             PG8_LDA(At, 0, 1); PG8_STAGE(PG8_SB(0, 0), b2, voffB); PG8_STAGE(PG8_SB(0, 1), b2 + hstep, voffB); PG8_STAGE(PG8_SA(0, 0), a2, voffA);
;             PG8_WAIT_V(8); PG8_WAIT_L(0); PG8_BAR; PG8_MMA(1, 0, At, B0); PG8_MMA(1, 1, At, B1); PG8_BAR; PG8_SCHED;
.LBB0_426:
	s_add_u32 s48, s40, s46
	s_addc_u32 s49, s41, s47
	s_add_u32 s48, s48, 0x100
	s_addc_u32 s49, s49, 0
	s_add_u32 s67, s62, s46
	s_addc_u32 s68, s63, s47
	s_add_i32 s69, 0, 0x10000
	s_cmpk_eq_i32 s46, 0xf00
	s_cselect_b32 s51, s39, s49
	s_cselect_b32 s50, s64, s48
	v_add_u32_e32 v144, s69, v148
	s_cselect_b32 s49, s37, s68
	s_cselect_b32 s48, s65, s67
	s_add_i32 s67, 0, 0x14000
	ds_read_b128 v[152:155], v144
	ds_read_b128 v[156:159], v144 offset:1024
	ds_read_b128 v[160:163], v144 offset:2048
	ds_read_b128 v[164:167], v144 offset:3072
	v_add_u32_e32 v144, s67, v148
	ds_read_b128 v[168:171], v144
	ds_read_b128 v[172:175], v144 offset:1024
	ds_read_b128 v[176:179], v144 offset:2048
	ds_read_b128 v[180:183], v144 offset:3072
	s_add_u32 s72, s40, s46
	s_addc_u32 s73, s41, s47
	s_add_u32 s72, s72, 0x80080
	s_addc_u32 s73, s73, 0
	s_add_i32 m0, s31, 0xc000
	ds_read_b128 v[184:187], v151
	ds_read_b128 v[188:191], v151 offset:1024
	ds_read_b128 v[192:195], v151 offset:2048
	ds_read_b128 v[210:213], v151 offset:3072
	ds_read_b128 v[214:217], v151 offset:4096
	ds_read_b128 v[218:221], v151 offset:5120
	ds_read_b128 v[222:225], v151 offset:6144
	ds_read_b128 v[226:229], v151 offset:7168
	global_load_lds_dwordx4 v136, s[72:73]
	s_add_i32 m0, s31, 0xe000
	s_nop 0
	global_load_lds_dwordx4 v138, s[72:73]
	s_waitcnt vmcnt(8)
	s_waitcnt lgkmcnt(0)
	s_barrier
	s_setprio 2
	s_waitcnt lgkmcnt(0)
	v_mfma_f32_16x16x32_bf16 v[128:131], v[152:155], v[184:187], v[128:131]
	v_mfma_f32_16x16x32_bf16 v[124:127], v[160:163], v[184:187], v[124:127]
	v_mfma_f32_16x16x32_bf16 v[120:123], v[152:155], v[192:195], v[120:123]
	v_mfma_f32_16x16x32_bf16 v[116:119], v[160:163], v[192:195], v[116:119]
	v_mfma_f32_16x16x32_bf16 v[112:115], v[152:155], v[214:217], v[112:115]
	v_mfma_f32_16x16x32_bf16 v[108:111], v[160:163], v[214:217], v[108:111]
	v_mfma_f32_16x16x32_bf16 v[104:107], v[152:155], v[222:225], v[104:107]
	v_mfma_f32_16x16x32_bf16 v[100:103], v[160:163], v[222:225], v[100:103]
	v_mfma_f32_16x16x32_bf16 v[128:131], v[156:159], v[188:191], v[128:131]
	v_mfma_f32_16x16x32_bf16 v[124:127], v[164:167], v[188:191], v[124:127]
	v_mfma_f32_16x16x32_bf16 v[120:123], v[156:159], v[210:213], v[120:123]
	v_mfma_f32_16x16x32_bf16 v[116:119], v[164:167], v[210:213], v[116:119]
	v_mfma_f32_16x16x32_bf16 v[112:115], v[156:159], v[218:221], v[112:115]
	v_mfma_f32_16x16x32_bf16 v[108:111], v[164:167], v[218:221], v[108:111]
	v_mfma_f32_16x16x32_bf16 v[104:107], v[156:159], v[226:229], v[104:107]
	v_mfma_f32_16x16x32_bf16 v[100:103], v[164:167], v[226:229], v[100:103]
	s_setprio 0
	s_setprio 2
	v_mfma_f32_16x16x32_bf16 v[96:99], v[168:171], v[184:187], v[96:99]
	v_mfma_f32_16x16x32_bf16 v[92:95], v[176:179], v[184:187], v[92:95]
	v_mfma_f32_16x16x32_bf16 v[88:91], v[168:171], v[192:195], v[88:91]
	v_mfma_f32_16x16x32_bf16 v[84:87], v[176:179], v[192:195], v[84:87]
	v_mfma_f32_16x16x32_bf16 v[80:83], v[168:171], v[214:217], v[80:83]
	v_mfma_f32_16x16x32_bf16 v[76:79], v[176:179], v[214:217], v[76:79]
	v_mfma_f32_16x16x32_bf16 v[72:75], v[168:171], v[222:225], v[72:75]
	v_mfma_f32_16x16x32_bf16 v[68:71], v[176:179], v[222:225], v[68:71]
	v_mfma_f32_16x16x32_bf16 v[96:99], v[172:175], v[188:191], v[96:99]
	v_mfma_f32_16x16x32_bf16 v[92:95], v[180:183], v[188:191], v[92:95]
	v_mfma_f32_16x16x32_bf16 v[88:91], v[172:175], v[210:213], v[88:91]
	v_mfma_f32_16x16x32_bf16 v[84:87], v[180:183], v[210:213], v[84:87]
	v_mfma_f32_16x16x32_bf16 v[80:83], v[172:175], v[218:221], v[80:83]
	v_mfma_f32_16x16x32_bf16 v[76:79], v[180:183], v[218:221], v[76:79]
	v_mfma_f32_16x16x32_bf16 v[72:75], v[172:175], v[226:229], v[72:75]
	v_mfma_f32_16x16x32_bf16 v[68:71], v[180:183], v[226:229], v[68:71]
	s_setprio 0
	s_barrier
	s_add_i32 s68, s69, s55
	s_mov_b32 m0, s68
	ds_read_b128 v[184:187], v151 offset:16384
	ds_read_b128 v[188:191], v151 offset:17408
	ds_read_b128 v[192:195], v151 offset:18432
	ds_read_b128 v[210:213], v151 offset:19456
	ds_read_b128 v[214:217], v151 offset:20480
	ds_read_b128 v[218:221], v151 offset:21504
	ds_read_b128 v[222:225], v151 offset:22528
	ds_read_b128 v[226:229], v151 offset:23552
	global_load_lds_dwordx4 v2, s[48:49]
	s_add_i32 m0, s68, 0x2000
	s_add_u32 s68, s48, 0x80000
	s_addc_u32 s69, s49, 0
	s_add_i32 s67, s67, s55
	global_load_lds_dwordx4 v134, s[48:49]
	s_mov_b32 m0, s67
	s_add_u32 s78, s50, s12
	s_addc_u32 s79, s51, s13
	global_load_lds_dwordx4 v2, s[68:69]
	s_add_i32 m0, s67, 0x2000
	s_nop 0
	global_load_lds_dwordx4 v134, s[68:69]
	s_mov_b32 m0, s31
	s_nop 0
	global_load_lds_dwordx4 v0, s[50:51]
	s_mov_b32 m0, s56
	s_nop 0
	global_load_lds_dwordx4 v132, s[50:51]
	s_waitcnt vmcnt(8)
	s_waitcnt lgkmcnt(0)
	s_barrier
; #define PG8_STAGE(bufoff, gbase, voff) do { _Pragma("unroll") for (int _i = 0; _i < 2; ++_i) \
;         __builtin_amdgcn_global_load_lds((const unsigned*)((const char*)(gbase) + (voff)[_i]), (LAS unsigned*)(lds + (bufoff) + ldsw + _i * 8192), 16, 0, 0); } while (0)
; #define PG8_LDA(dst, b, h) do { _Pragma("unroll") for (int m = 0; m < 4; ++m) _Pragma("unroll") for (int k = 0; k < 2; ++k) dst[m][k] = *(const LAS bf16x8*)(lds + PG8_SA(b, h) + aoff + m * 2048 + k * 1024); } while (0)
; #define PG8_LDB(dst, b, h) do { _Pragma("unroll") for (int n = 0; n < 2; ++n) _Pragma("unroll") for (int k = 0; k < 2; ++k) dst[n][k] = *(const LAS bf16x8*)(lds + PG8_SB(b, h) + boff + n * 2048 + k * 1024); } while (0)
; #define PG8_MMA(ai, bj, At, Bt) do { __builtin_amdgcn_s_setprio(2); _Pragma("unroll") for (int m = 0; m < 4; ++m) _Pragma("unroll") for (int n = 0; n < 2; ++n) _Pragma("unroll") for (int k = 0; k < 2; ++k) \
;         acc[ai][bj][m][n] = __builtin_amdgcn_mfma_f32_16x16x32_bf16(Bt[n][k], At[m][k], acc[ai][bj][m][n], 0, 0, 0); __builtin_amdgcn_s_setprio(0); } while (0)
; #define PG8_WAIT_V(n) asm volatile("s_waitcnt vmcnt(" #n ")" ::: "memory")
; #define PG8_WAIT_L(n) asm volatile("s_waitcnt lgkmcnt(" #n ")" ::: "memory")
; #define PG8_BAR __builtin_amdgcn_s_barrier()
; #define PG8_SCHED __builtin_amdgcn_sched_barrier(0)
; template <class Epi>
; __device__ __forceinline__ void gemm_phase(const Lt& lt, LAS unsigned char* lds, const Gemm g, const StaticOrder& S, const Epi& E) {
;     ...
;             PG8_LDA(At, 0, 1); PG8_STAGE(PG8_SB(0, 0), b2, voffB); PG8_STAGE(PG8_SB(0, 1), b2 + hstep, voffB); PG8_STAGE(PG8_SA(0, 0), a2, voffA);
;             PG8_WAIT_V(8); PG8_WAIT_L(0); PG8_BAR; PG8_MMA(1, 0, At, B0); PG8_MMA(1, 1, At, B1); PG8_BAR; PG8_SCHED;
;             PG8_LDB(B0, 1, 0); PG8_LDB(B1, 1, 1); PG8_SCHED; PG8_LDA(At, 1, 0); PG8_STAGE(PG8_SA(0, 1), a2 + hstep, voffA);
;             PG8_WAIT_V(8); PG8_WAIT_L(0); PG8_BAR; PG8_MMA(0, 0, At, B0); PG8_MMA(0, 1, At, B1); PG8_BAR; PG8_SCHED;
	s_setprio 2
	s_waitcnt lgkmcnt(0)
	v_mfma_f32_16x16x32_bf16 v[64:67], v[152:155], v[184:187], v[64:67]
	v_mfma_f32_16x16x32_bf16 v[60:63], v[160:163], v[184:187], v[60:63]
	v_mfma_f32_16x16x32_bf16 v[56:59], v[152:155], v[192:195], v[56:59]
	v_mfma_f32_16x16x32_bf16 v[52:55], v[160:163], v[192:195], v[52:55]
	v_mfma_f32_16x16x32_bf16 v[48:51], v[152:155], v[214:217], v[48:51]
	v_mfma_f32_16x16x32_bf16 v[44:47], v[160:163], v[214:217], v[44:47]
	v_mfma_f32_16x16x32_bf16 v[40:43], v[152:155], v[222:225], v[40:43]
	v_mfma_f32_16x16x32_bf16 v[36:39], v[160:163], v[222:225], v[36:39]
	v_mfma_f32_16x16x32_bf16 v[64:67], v[156:159], v[188:191], v[64:67]
	v_mfma_f32_16x16x32_bf16 v[60:63], v[164:167], v[188:191], v[60:63]
	v_mfma_f32_16x16x32_bf16 v[56:59], v[156:159], v[210:213], v[56:59]
	v_mfma_f32_16x16x32_bf16 v[52:55], v[164:167], v[210:213], v[52:55]
	v_mfma_f32_16x16x32_bf16 v[48:51], v[156:159], v[218:221], v[48:51]
	v_mfma_f32_16x16x32_bf16 v[44:47], v[164:167], v[218:221], v[44:47]
	v_mfma_f32_16x16x32_bf16 v[40:43], v[156:159], v[226:229], v[40:43]
	v_mfma_f32_16x16x32_bf16 v[36:39], v[164:167], v[226:229], v[36:39]
	s_setprio 0
	s_setprio 2
	v_mfma_f32_16x16x32_bf16 v[32:35], v[168:171], v[184:187], v[32:35]
	v_mfma_f32_16x16x32_bf16 v[28:31], v[176:179], v[184:187], v[28:31]
	v_mfma_f32_16x16x32_bf16 v[24:27], v[168:171], v[192:195], v[24:27]
	v_mfma_f32_16x16x32_bf16 v[20:23], v[176:179], v[192:195], v[20:23]
	v_mfma_f32_16x16x32_bf16 v[16:19], v[168:171], v[214:217], v[16:19]
	v_mfma_f32_16x16x32_bf16 v[12:15], v[176:179], v[214:217], v[12:15]
	v_mfma_f32_16x16x32_bf16 v[8:11], v[168:171], v[222:225], v[8:11]
	v_mfma_f32_16x16x32_bf16 v[4:7], v[176:179], v[222:225], v[4:7]
	v_mfma_f32_16x16x32_bf16 v[32:35], v[172:175], v[188:191], v[32:35]
	v_mfma_f32_16x16x32_bf16 v[28:31], v[180:183], v[188:191], v[28:31]
	v_mfma_f32_16x16x32_bf16 v[24:27], v[172:175], v[210:213], v[24:27]
	v_mfma_f32_16x16x32_bf16 v[20:23], v[180:183], v[210:213], v[20:23]
	v_mfma_f32_16x16x32_bf16 v[16:19], v[172:175], v[218:221], v[16:19]
	v_mfma_f32_16x16x32_bf16 v[12:15], v[180:183], v[218:221], v[12:15]
	v_mfma_f32_16x16x32_bf16 v[8:11], v[172:175], v[226:229], v[8:11]
	v_mfma_f32_16x16x32_bf16 v[4:7], v[180:183], v[226:229], v[4:7]
	s_setprio 0
	s_barrier
	s_add_i32 s67, 0, 0x18000
	s_add_i32 s68, 0, 0x1c000
	v_add_u32_e32 v164, s67, v148
	v_add_u32_e32 v180, s68, v148
	ds_read_b128 v[152:155], v164
	ds_read_b128 v[156:159], v164 offset:1024
	ds_read_b128 v[160:163], v164 offset:2048
	ds_read_b128 v[164:167], v164 offset:3072
	ds_read_b128 v[168:171], v180
	ds_read_b128 v[172:175], v180 offset:1024
	ds_read_b128 v[176:179], v180 offset:2048
	ds_read_b128 v[180:183], v180 offset:3072
	s_add_u32 s50, s50, 0x80000
	s_addc_u32 s51, s51, 0
	s_mov_b32 m0, s57
	ds_read_b128 v[184:187], v151 offset:32768
	ds_read_b128 v[188:191], v151 offset:33792
	ds_read_b128 v[192:195], v151 offset:34816
	ds_read_b128 v[210:213], v151 offset:35840
	ds_read_b128 v[214:217], v151 offset:36864
	ds_read_b128 v[218:221], v151 offset:37888
	ds_read_b128 v[222:225], v151 offset:38912
	ds_read_b128 v[226:229], v151 offset:39936
	global_load_lds_dwordx4 v0, s[50:51]
	s_mov_b32 m0, s58
	s_nop 0
	global_load_lds_dwordx4 v132, s[50:51]
	s_waitcnt vmcnt(8)
	s_waitcnt lgkmcnt(0)
	s_barrier
	s_setprio 2
	s_waitcnt lgkmcnt(0)
	v_mfma_f32_16x16x32_bf16 v[128:131], v[152:155], v[184:187], v[128:131]
	v_mfma_f32_16x16x32_bf16 v[124:127], v[160:163], v[184:187], v[124:127]
	v_mfma_f32_16x16x32_bf16 v[120:123], v[152:155], v[192:195], v[120:123]
	v_mfma_f32_16x16x32_bf16 v[116:119], v[160:163], v[192:195], v[116:119]
	v_mfma_f32_16x16x32_bf16 v[112:115], v[152:155], v[214:217], v[112:115]
	v_mfma_f32_16x16x32_bf16 v[108:111], v[160:163], v[214:217], v[108:111]
	v_mfma_f32_16x16x32_bf16 v[104:107], v[152:155], v[222:225], v[104:107]
	v_mfma_f32_16x16x32_bf16 v[100:103], v[160:163], v[222:225], v[100:103]
	v_mfma_f32_16x16x32_bf16 v[128:131], v[156:159], v[188:191], v[128:131]
	v_mfma_f32_16x16x32_bf16 v[124:127], v[164:167], v[188:191], v[124:127]
	v_mfma_f32_16x16x32_bf16 v[120:123], v[156:159], v[210:213], v[120:123]
	v_mfma_f32_16x16x32_bf16 v[116:119], v[164:167], v[210:213], v[116:119]
	v_mfma_f32_16x16x32_bf16 v[112:115], v[156:159], v[218:221], v[112:115]
	v_mfma_f32_16x16x32_bf16 v[108:111], v[164:167], v[218:221], v[108:111]
	v_mfma_f32_16x16x32_bf16 v[104:107], v[156:159], v[226:229], v[104:107]
	v_mfma_f32_16x16x32_bf16 v[100:103], v[164:167], v[226:229], v[100:103]
	s_setprio 0
	s_setprio 2
	v_mfma_f32_16x16x32_bf16 v[96:99], v[168:171], v[184:187], v[96:99]
	v_mfma_f32_16x16x32_bf16 v[92:95], v[176:179], v[184:187], v[92:95]
	v_mfma_f32_16x16x32_bf16 v[88:91], v[168:171], v[192:195], v[88:91]
	v_mfma_f32_16x16x32_bf16 v[84:87], v[176:179], v[192:195], v[84:87]
	v_mfma_f32_16x16x32_bf16 v[80:83], v[168:171], v[214:217], v[80:83]
	v_mfma_f32_16x16x32_bf16 v[76:79], v[176:179], v[214:217], v[76:79]
	v_mfma_f32_16x16x32_bf16 v[72:75], v[168:171], v[222:225], v[72:75]
	v_mfma_f32_16x16x32_bf16 v[68:71], v[176:179], v[222:225], v[68:71]
	v_mfma_f32_16x16x32_bf16 v[96:99], v[172:175], v[188:191], v[96:99]
	v_mfma_f32_16x16x32_bf16 v[92:95], v[180:183], v[188:191], v[92:95]
	v_mfma_f32_16x16x32_bf16 v[88:91], v[172:175], v[210:213], v[88:91]
	v_mfma_f32_16x16x32_bf16 v[84:87], v[180:183], v[210:213], v[84:87]
	v_mfma_f32_16x16x32_bf16 v[80:83], v[172:175], v[218:221], v[80:83]
	v_mfma_f32_16x16x32_bf16 v[76:79], v[180:183], v[218:221], v[76:79]
	v_mfma_f32_16x16x32_bf16 v[72:75], v[172:175], v[226:229], v[72:75]
	v_mfma_f32_16x16x32_bf16 v[68:71], v[180:183], v[226:229], v[68:71]
	s_setprio 0
	s_barrier
; #define LAS __attribute__((address_space(3)))
; __device__ __forceinline__ unsigned cvt_pk_bf16(float lo, float hi) { const f32x2 v = {lo, hi}; return __builtin_bit_cast(unsigned, __builtin_convertvector(v, bf16x2_t)); }
; #define PG8_STAGE(bufoff, gbase, voff) do { _Pragma("unroll") for (int _i = 0; _i < 2; ++_i) \
;         __builtin_amdgcn_global_load_lds((const unsigned*)((const char*)(gbase) + (voff)[_i]), (LAS unsigned*)(lds + (bufoff) + ldsw + _i * 8192), 16, 0, 0); } while (0)
; template <class Epi>
; __device__ __forceinline__ void gemm_phase(const Lt& lt, LAS unsigned char* lds, const Gemm g, const StaticOrder& S, const Epi& E) {
;     ...
;             PG8_LDA(At, 1, 1); PG8_STAGE(PG8_SB(1, 0), b3, voffB); PG8_STAGE(PG8_SB(1, 1), b3 + hstep, voffB); PG8_STAGE(PG8_SA(1, 0), a3, voffA);
;             PG8_WAIT_V(8); PG8_WAIT_L(0); PG8_BAR; PG8_MMA(1, 0, At, B0); PG8_MMA(1, 1, At, B1); PG8_BAR; PG8_SCHED;
;         }
;         E(acc, cur, wr, wc, fr, fq, lds, ui & 7);
;     __device__ __forceinline__ void operator()(const f32x4 (&acc)[2][2][4][2], const pg8::Unit& u, int wr, int wc, int fr, int fq, LAS unsigned char* lds, int buf) const {
;         const int row0 = u.pm * 256 + wr * 64 + fr, col0 = u.pn * 256 + wc * 32 + 8 * fq;
;         const LAS float* rst = (const LAS float*)(lds + pg8::STAGE_BYTES) + buf * 256 + wr * 64 + fr;
;         float rs[2][4];
; #pragma unroll
;         for (int ai = 0; ai < 2; ++ai)
; #pragma unroll
;             for (int m = 0; m < 4; ++m) rs[ai][m] = rst[ai * 128 + m * 16];
; #pragma unroll
;         for (int ai = 0; ai < 2; ++ai)
; #pragma unroll
;             for (int m = 0; m < 4; ++m) {
;                 const int row = row0 + ai * 128 + m * 16;
;                 bf16_t* rowp = O + (size_t)row * ldc + col0;
; #pragma unroll
;                 for (int bj = 0; bj < 2; ++bj) {
;                     f32x4 v0 = acc[ai][bj][m][0] * rs[ai][m], v1 = acc[ai][bj][m][1] * rs[ai][m];
;                     if (ACT == 1) {
; #pragma unroll
;                         for (int j = 0; j < 4; ++j) { const float a = fmaxf(v0[j], 0.f), b = fmaxf(v1[j], 0.f); v0[j] = a * a; v1[j] = b * b; }
;                     }
;                     u32x4 w; w.x = cvt_pk_bf16(v0[0], v0[1]); w.y = cvt_pk_bf16(v0[2], v0[3]); w.z = cvt_pk_bf16(v1[0], v1[1]); w.w = cvt_pk_bf16(v1[2], v1[3]);
;                     *(u32x4*)(rowp + bj * 128) = w;
	s_add_i32 s50, s67, s55
	s_add_u32 s72, s48, s12
	s_addc_u32 s73, s49, s13
	s_mov_b32 m0, s50
	ds_read_b128 v[184:187], v151 offset:49152
	ds_read_b128 v[188:191], v151 offset:50176
	ds_read_b128 v[192:195], v151 offset:51200
	ds_read_b128 v[210:213], v151 offset:52224
	ds_read_b128 v[214:217], v151 offset:53248
	ds_read_b128 v[218:221], v151 offset:54272
	ds_read_b128 v[222:225], v151 offset:55296
	ds_read_b128 v[226:229], v151 offset:56320
	global_load_lds_dwordx4 v2, s[72:73]
	s_add_i32 m0, s50, 0x2000
	s_add_u32 s48, s48, 0x80080
	s_addc_u32 s49, s49, 0
	s_add_i32 s50, s68, s55
	global_load_lds_dwordx4 v134, s[72:73]
	s_mov_b32 m0, s50
	s_nop 0
	global_load_lds_dwordx4 v2, s[48:49]
	s_add_i32 m0, s50, 0x2000
	s_nop 0
	global_load_lds_dwordx4 v134, s[48:49]
	s_mov_b32 m0, s59
	s_nop 0
	global_load_lds_dwordx4 v0, s[78:79]
	s_mov_b32 m0, s60
	s_nop 0
	global_load_lds_dwordx4 v132, s[78:79]
	s_waitcnt vmcnt(8)
	s_waitcnt lgkmcnt(0)
	s_barrier
	s_setprio 2
	s_waitcnt lgkmcnt(0)
	v_mfma_f32_16x16x32_bf16 v[64:67], v[152:155], v[184:187], v[64:67]
	v_mfma_f32_16x16x32_bf16 v[60:63], v[160:163], v[184:187], v[60:63]
	v_mfma_f32_16x16x32_bf16 v[56:59], v[152:155], v[192:195], v[56:59]
	v_mfma_f32_16x16x32_bf16 v[52:55], v[160:163], v[192:195], v[52:55]
	v_mfma_f32_16x16x32_bf16 v[48:51], v[152:155], v[214:217], v[48:51]
	v_mfma_f32_16x16x32_bf16 v[44:47], v[160:163], v[214:217], v[44:47]
	v_mfma_f32_16x16x32_bf16 v[40:43], v[152:155], v[222:225], v[40:43]
	v_mfma_f32_16x16x32_bf16 v[36:39], v[160:163], v[222:225], v[36:39]
	v_mfma_f32_16x16x32_bf16 v[64:67], v[156:159], v[188:191], v[64:67]
	v_mfma_f32_16x16x32_bf16 v[60:63], v[164:167], v[188:191], v[60:63]
	v_mfma_f32_16x16x32_bf16 v[56:59], v[156:159], v[210:213], v[56:59]
	v_mfma_f32_16x16x32_bf16 v[52:55], v[164:167], v[210:213], v[52:55]
	v_mfma_f32_16x16x32_bf16 v[48:51], v[156:159], v[218:221], v[48:51]
	v_mfma_f32_16x16x32_bf16 v[44:47], v[164:167], v[218:221], v[44:47]
	v_mfma_f32_16x16x32_bf16 v[40:43], v[156:159], v[226:229], v[40:43]
	v_mfma_f32_16x16x32_bf16 v[36:39], v[164:167], v[226:229], v[36:39]
	s_setprio 0
	s_setprio 2
	v_mfma_f32_16x16x32_bf16 v[32:35], v[168:171], v[184:187], v[32:35]
	v_mfma_f32_16x16x32_bf16 v[28:31], v[176:179], v[184:187], v[28:31]
	v_mfma_f32_16x16x32_bf16 v[24:27], v[168:171], v[192:195], v[24:27]
	v_mfma_f32_16x16x32_bf16 v[20:23], v[176:179], v[192:195], v[20:23]
	v_mfma_f32_16x16x32_bf16 v[16:19], v[168:171], v[214:217], v[16:19]
	v_mfma_f32_16x16x32_bf16 v[12:15], v[176:179], v[214:217], v[12:15]
	v_mfma_f32_16x16x32_bf16 v[8:11], v[168:171], v[222:225], v[8:11]
	v_mfma_f32_16x16x32_bf16 v[4:7], v[176:179], v[222:225], v[4:7]
	v_mfma_f32_16x16x32_bf16 v[32:35], v[172:175], v[188:191], v[32:35]
	v_mfma_f32_16x16x32_bf16 v[28:31], v[180:183], v[188:191], v[28:31]
	v_mfma_f32_16x16x32_bf16 v[24:27], v[172:175], v[210:213], v[24:27]
	v_mfma_f32_16x16x32_bf16 v[20:23], v[180:183], v[210:213], v[20:23]
	v_mfma_f32_16x16x32_bf16 v[16:19], v[172:175], v[218:221], v[16:19]
	v_mfma_f32_16x16x32_bf16 v[12:15], v[180:183], v[218:221], v[12:15]
	v_mfma_f32_16x16x32_bf16 v[8:11], v[172:175], v[226:229], v[8:11]
	v_mfma_f32_16x16x32_bf16 v[4:7], v[180:183], v[226:229], v[4:7]
	s_setprio 0
	s_barrier
	s_add_i32 s66, s66, 2
	s_add_u32 s46, s46, 0x100
	s_addc_u32 s47, s47, 0
	s_cmp_gt_u32 s66, 29
	s_cbranch_scc0 .LBB0_426
	s_add_u32 s46, s62, 0xffffff00
	s_addc_u32 s47, s63, -1
	s_lshl_b32 s37, s29, 10
	s_and_b32 s37, s37, 0x1c00
	v_add_u32_e32 v140, s37, v149
	v_lshl_or_b32 v144, s30, 8, v150
	v_lshl_add_u32 v168, s28, 8, v147
	ds_read2_b32 v[156:157], v140 offset1:16
	ds_read2_b32 v[158:159], v140 offset0:32 offset1:48
	ds_read2_b32 v[160:161], v140 offset0:128 offset1:144
	ds_read2_b32 v[140:141], v140 offset0:160 offset1:176
	v_ashrrev_i32_e32 v145, 31, v144
	v_mov_b64_e32 v[142:143], s[34:35]
	v_mad_i64_i32 v[152:153], s[48:49], v168, s76, v[142:143]
	v_lshlrev_b64 v[144:145], 1, v[144:145]
	v_lshl_add_u64 v[162:163], v[152:153], 0, v[144:145]
	s_waitcnt lgkmcnt(0)
	v_pk_mul_f32 v[154:155], v[130:131], v[156:157] op_sel_hi:[1,0]
	v_pk_mul_f32 v[152:153], v[128:129], v[156:157] op_sel_hi:[1,0]
	v_pk_mul_f32 v[164:165], v[126:127], v[156:157] op_sel_hi:[1,0]
	v_pk_mul_f32 v[166:167], v[124:125], v[156:157] op_sel_hi:[1,0]
	v_cvt_pk_bf16_f32 v152, v152, v153
	v_cvt_pk_bf16_f32 v153, v154, v155
	v_cvt_pk_bf16_f32 v154, v166, v167
	v_cvt_pk_bf16_f32 v155, v164, v165
	global_store_dwordx4 v[162:163], v[152:155], off
	v_pk_mul_f32 v[164:165], v[94:95], v[156:157] op_sel_hi:[1,0]
	v_pk_mul_f32 v[166:167], v[92:93], v[156:157] op_sel_hi:[1,0]
	v_pk_mul_f32 v[154:155], v[98:99], v[156:157] op_sel_hi:[1,0]
	v_pk_mul_f32 v[152:153], v[96:97], v[156:157] op_sel_hi:[1,0]
	v_mov_b32_e32 v156, v157
	v_cvt_pk_bf16_f32 v152, v152, v153
	v_cvt_pk_bf16_f32 v153, v154, v155
	v_cvt_pk_bf16_f32 v154, v166, v167
	v_cvt_pk_bf16_f32 v155, v164, v165
	global_store_dwordx4 v[162:163], v[152:155], off offset:256
	v_pk_mul_f32 v[164:165], v[118:119], v[156:157] op_sel_hi:[1,0]
	v_pk_mul_f32 v[166:167], v[116:117], v[156:157] op_sel_hi:[1,0]
	v_or_b32_e32 v152, 16, v168
	v_mad_i64_i32 v[152:153], s[48:49], v152, s76, v[142:143]
	v_lshl_add_u64 v[162:163], v[152:153], 0, v[144:145]
	v_pk_mul_f32 v[154:155], v[122:123], v[156:157] op_sel_hi:[1,0]
	v_pk_mul_f32 v[152:153], v[120:121], v[156:157] op_sel_hi:[1,0]
	s_and_b64 vcc, vcc, exec
	v_cvt_pk_bf16_f32 v152, v152, v153
	v_cvt_pk_bf16_f32 v153, v154, v155
	v_cvt_pk_bf16_f32 v154, v166, v167
	v_cvt_pk_bf16_f32 v155, v164, v165
	global_store_dwordx4 v[162:163], v[152:155], off
	v_pk_mul_f32 v[164:165], v[86:87], v[156:157] op_sel_hi:[1,0]
; __device__ __forceinline__ unsigned cvt_pk_bf16(float lo, float hi) { const f32x2 v = {lo, hi}; return __builtin_bit_cast(unsigned, __builtin_convertvector(v, bf16x2_t)); }
;     __device__ __forceinline__ void operator()(const f32x4 (&acc)[2][2][4][2], const pg8::Unit& u, int wr, int wc, int fr, int fq, LAS unsigned char* lds, int buf) const {
;     ...
;         for (int ai = 0; ai < 2; ++ai)
; #pragma unroll
;             for (int m = 0; m < 4; ++m) {
;                 const int row = row0 + ai * 128 + m * 16;
;                 bf16_t* rowp = O + (size_t)row * ldc + col0;
; #pragma unroll
;                 for (int bj = 0; bj < 2; ++bj) {
;                     f32x4 v0 = acc[ai][bj][m][0] * rs[ai][m], v1 = acc[ai][bj][m][1] * rs[ai][m];
;                     if (ACT == 1) {
; #pragma unroll
;                         for (int j = 0; j < 4; ++j) { const float a = fmaxf(v0[j], 0.f), b = fmaxf(v1[j], 0.f); v0[j] = a * a; v1[j] = b * b; }
;                     }
;                     u32x4 w; w.x = cvt_pk_bf16(v0[0], v0[1]); w.y = cvt_pk_bf16(v0[2], v0[3]); w.z = cvt_pk_bf16(v1[0], v1[1]); w.w = cvt_pk_bf16(v1[2], v1[3]);
;                     *(u32x4*)(rowp + bj * 128) = w;
;                 }
	s_nop 0
	v_pk_mul_f32 v[154:155], v[90:91], v[156:157] op_sel_hi:[1,0]
	v_pk_mul_f32 v[152:153], v[88:89], v[156:157] op_sel_hi:[1,0]
	v_pk_mul_f32 v[156:157], v[84:85], v[156:157] op_sel_hi:[1,0]
	v_cvt_pk_bf16_f32 v152, v152, v153
	v_cvt_pk_bf16_f32 v153, v154, v155
	v_cvt_pk_bf16_f32 v154, v156, v157
	v_cvt_pk_bf16_f32 v155, v164, v165
	global_store_dwordx4 v[162:163], v[152:155], off offset:256
	v_pk_mul_f32 v[162:163], v[110:111], v[158:159] op_sel_hi:[1,0]
	v_pk_mul_f32 v[164:165], v[108:109], v[158:159] op_sel_hi:[1,0]
	v_or_b32_e32 v152, 32, v168
	v_mad_i64_i32 v[152:153], s[48:49], v152, s76, v[142:143]
	v_lshl_add_u64 v[156:157], v[152:153], 0, v[144:145]
	v_pk_mul_f32 v[154:155], v[114:115], v[158:159] op_sel_hi:[1,0]
	v_pk_mul_f32 v[152:153], v[112:113], v[158:159] op_sel_hi:[1,0]
	s_nop 0
	v_cvt_pk_bf16_f32 v152, v152, v153
	v_cvt_pk_bf16_f32 v153, v154, v155
	v_cvt_pk_bf16_f32 v154, v164, v165
	v_cvt_pk_bf16_f32 v155, v162, v163
	global_store_dwordx4 v[156:157], v[152:155], off
	v_pk_mul_f32 v[162:163], v[78:79], v[158:159] op_sel_hi:[1,0]
	v_pk_mul_f32 v[164:165], v[76:77], v[158:159] op_sel_hi:[1,0]
	v_pk_mul_f32 v[154:155], v[82:83], v[158:159] op_sel_hi:[1,0]
	v_pk_mul_f32 v[152:153], v[80:81], v[158:159] op_sel_hi:[1,0]
	v_mov_b32_e32 v158, v159
	v_cvt_pk_bf16_f32 v152, v152, v153
	v_cvt_pk_bf16_f32 v153, v154, v155
	v_cvt_pk_bf16_f32 v154, v164, v165
	v_cvt_pk_bf16_f32 v155, v162, v163
	global_store_dwordx4 v[156:157], v[152:155], off offset:256
	v_pk_mul_f32 v[162:163], v[102:103], v[158:159] op_sel_hi:[1,0]
	v_pk_mul_f32 v[164:165], v[100:101], v[158:159] op_sel_hi:[1,0]
	v_or_b32_e32 v152, 48, v168
	v_mad_i64_i32 v[152:153], s[48:49], v152, s76, v[142:143]
	v_lshl_add_u64 v[156:157], v[152:153], 0, v[144:145]
	v_pk_mul_f32 v[154:155], v[106:107], v[158:159] op_sel_hi:[1,0]
	v_pk_mul_f32 v[152:153], v[104:105], v[158:159] op_sel_hi:[1,0]
	s_nop 0
	v_cvt_pk_bf16_f32 v152, v152, v153
	v_cvt_pk_bf16_f32 v153, v154, v155
	v_cvt_pk_bf16_f32 v154, v164, v165
	v_cvt_pk_bf16_f32 v155, v162, v163
	global_store_dwordx4 v[156:157], v[152:155], off
	v_pk_mul_f32 v[162:163], v[70:71], v[158:159] op_sel_hi:[1,0]
	s_nop 0
	v_pk_mul_f32 v[154:155], v[74:75], v[158:159] op_sel_hi:[1,0]
	v_pk_mul_f32 v[152:153], v[72:73], v[158:159] op_sel_hi:[1,0]
	v_pk_mul_f32 v[158:159], v[68:69], v[158:159] op_sel_hi:[1,0]
	v_cvt_pk_bf16_f32 v152, v152, v153
	v_cvt_pk_bf16_f32 v153, v154, v155
	v_cvt_pk_bf16_f32 v154, v158, v159
	v_cvt_pk_bf16_f32 v155, v162, v163
	global_store_dwordx4 v[156:157], v[152:155], off offset:256
	v_pk_mul_f32 v[158:159], v[62:63], v[160:161] op_sel_hi:[1,0]
	v_pk_mul_f32 v[162:163], v[60:61], v[160:161] op_sel_hi:[1,0]
	v_add_u32_e32 v152, 0x80, v168
	v_mad_i64_i32 v[152:153], s[48:49], v152, s76, v[142:143]
	v_lshl_add_u64 v[156:157], v[152:153], 0, v[144:145]
	v_pk_mul_f32 v[154:155], v[66:67], v[160:161] op_sel_hi:[1,0]
	v_pk_mul_f32 v[152:153], v[64:65], v[160:161] op_sel_hi:[1,0]
	s_nop 0
	v_cvt_pk_bf16_f32 v152, v152, v153
	v_cvt_pk_bf16_f32 v153, v154, v155
	v_cvt_pk_bf16_f32 v154, v162, v163
	v_cvt_pk_bf16_f32 v155, v158, v159
	global_store_dwordx4 v[156:157], v[152:155], off
	v_pk_mul_f32 v[158:159], v[30:31], v[160:161] op_sel_hi:[1,0]
	v_pk_mul_f32 v[162:163], v[28:29], v[160:161] op_sel_hi:[1,0]
	v_pk_mul_f32 v[154:155], v[34:35], v[160:161] op_sel_hi:[1,0]
	v_pk_mul_f32 v[152:153], v[32:33], v[160:161] op_sel_hi:[1,0]
	s_nop 0
	v_cvt_pk_bf16_f32 v152, v152, v153
	v_cvt_pk_bf16_f32 v153, v154, v155
	v_cvt_pk_bf16_f32 v154, v162, v163
	v_cvt_pk_bf16_f32 v155, v158, v159
	global_store_dwordx4 v[156:157], v[152:155], off offset:256
	v_mov_b32_e32 v158, v161
	v_pk_mul_f32 v[160:161], v[54:55], v[158:159] op_sel_hi:[1,0]
	v_add_u32_e32 v152, 0x90, v168
	v_mad_i64_i32 v[152:153], s[48:49], v152, s76, v[142:143]
	v_lshl_add_u64 v[156:157], v[152:153], 0, v[144:145]
	v_pk_mul_f32 v[154:155], v[58:59], v[158:159] op_sel_hi:[1,0]
	v_pk_mul_f32 v[152:153], v[56:57], v[158:159] op_sel_hi:[1,0]
	v_pk_mul_f32 v[162:163], v[52:53], v[158:159] op_sel_hi:[1,0]
	v_cvt_pk_bf16_f32 v152, v152, v153
	v_cvt_pk_bf16_f32 v153, v154, v155
	v_cvt_pk_bf16_f32 v154, v162, v163
	v_cvt_pk_bf16_f32 v155, v160, v161
	global_store_dwordx4 v[156:157], v[152:155], off
	v_pk_mul_f32 v[160:161], v[22:23], v[158:159] op_sel_hi:[1,0]
	s_nop 0
	v_pk_mul_f32 v[154:155], v[26:27], v[158:159] op_sel_hi:[1,0]
	v_pk_mul_f32 v[152:153], v[24:25], v[158:159] op_sel_hi:[1,0]
	v_pk_mul_f32 v[158:159], v[20:21], v[158:159] op_sel_hi:[1,0]
	v_cvt_pk_bf16_f32 v152, v152, v153
	v_cvt_pk_bf16_f32 v153, v154, v155
	v_cvt_pk_bf16_f32 v154, v158, v159
	v_cvt_pk_bf16_f32 v155, v160, v161
	global_store_dwordx4 v[156:157], v[152:155], off offset:256
	v_pk_mul_f32 v[158:159], v[46:47], v[140:141] op_sel_hi:[1,0]
	v_pk_mul_f32 v[160:161], v[44:45], v[140:141] op_sel_hi:[1,0]
	v_add_u32_e32 v152, 0xa0, v168
	v_mad_i64_i32 v[152:153], s[48:49], v152, s76, v[142:143]
	v_lshl_add_u64 v[156:157], v[152:153], 0, v[144:145]
	v_pk_mul_f32 v[154:155], v[50:51], v[140:141] op_sel_hi:[1,0]
	v_pk_mul_f32 v[152:153], v[48:49], v[140:141] op_sel_hi:[1,0]
	s_nop 0
	v_cvt_pk_bf16_f32 v152, v152, v153
	v_cvt_pk_bf16_f32 v153, v154, v155
	v_cvt_pk_bf16_f32 v154, v160, v161
	v_cvt_pk_bf16_f32 v155, v158, v159
	global_store_dwordx4 v[156:157], v[152:155], off
	v_pk_mul_f32 v[158:159], v[14:15], v[140:141] op_sel_hi:[1,0]
	v_pk_mul_f32 v[160:161], v[12:13], v[140:141] op_sel_hi:[1,0]
	v_pk_mul_f32 v[154:155], v[18:19], v[140:141] op_sel_hi:[1,0]
	v_pk_mul_f32 v[152:153], v[16:17], v[140:141] op_sel_hi:[1,0]
	v_add_u32_e32 v140, 0xb0, v168
	v_cvt_pk_bf16_f32 v152, v152, v153
	v_cvt_pk_bf16_f32 v153, v154, v155
	v_cvt_pk_bf16_f32 v154, v160, v161
	v_cvt_pk_bf16_f32 v155, v158, v159
	global_store_dwordx4 v[156:157], v[152:155], off offset:256
	v_mad_i64_i32 v[142:143], s[48:49], v140, s76, v[142:143]
	s_nop 0
	v_mov_b32_e32 v152, v141
	v_lshl_add_u64 v[144:145], v[142:143], 0, v[144:145]
	v_pk_mul_f32 v[142:143], v[42:43], v[152:153] op_sel_hi:[1,0]
	v_pk_mul_f32 v[140:141], v[40:41], v[152:153] op_sel_hi:[1,0]
	v_pk_mul_f32 v[154:155], v[38:39], v[152:153] op_sel_hi:[1,0]
	v_pk_mul_f32 v[156:157], v[36:37], v[152:153] op_sel_hi:[1,0]
	v_cvt_pk_bf16_f32 v140, v140, v141
	v_cvt_pk_bf16_f32 v141, v142, v143
	v_cvt_pk_bf16_f32 v142, v156, v157
	v_cvt_pk_bf16_f32 v143, v154, v155
	global_store_dwordx4 v[144:145], v[140:143], off
	v_pk_mul_f32 v[154:155], v[6:7], v[152:153] op_sel_hi:[1,0]
	s_nop 0
	v_pk_mul_f32 v[142:143], v[10:11], v[152:153] op_sel_hi:[1,0]
	v_pk_mul_f32 v[140:141], v[8:9], v[152:153] op_sel_hi:[1,0]
	v_pk_mul_f32 v[152:153], v[4:5], v[152:153] op_sel_hi:[1,0]
	v_cvt_pk_bf16_f32 v140, v140, v141
	v_cvt_pk_bf16_f32 v141, v142, v143
	v_cvt_pk_bf16_f32 v142, v152, v153
	v_cvt_pk_bf16_f32 v143, v154, v155
	global_store_dwordx4 v[144:145], v[140:143], off offset:256
	s_cbranch_vccz .LBB0_430
; #define LAS __attribute__((address_space(3)))
; __device__ __forceinline__ float row_rstd(const float* ssq, int row, float inv_n) {
;     const f32x4* p = (const f32x4*)(ssq + (size_t)row * 32);
;     f32x4 s = p[0];
; #pragma unroll
;     for (int i = 1; i < 8; ++i) s += p[i];
;     return rsqrtf((s[0] + s[1] + s[2] + s[3]) * inv_n + NORM_EPS);
; }
;     __device__ __forceinline__ void prepare(const pg8::Unit& u, LAS unsigned char* lds, int buf, int tid) const {
;         if (tid < 256) ((LAS float*)(lds + pg8::STAGE_BYTES))[buf * 256 + tid] = row_rstd(ssq, u.pm * 256 + tid, 1.0f / DM);
;     }
	s_cmp_gt_i32 s29, 6
	s_cselect_b64 s[28:29], -1, 0
	s_and_b64 s[40:41], s[28:29], s[0:1]
	s_and_saveexec_b64 s[28:29], s[40:41]
	s_cbranch_execz .LBB0_422
	v_lshl_add_u32 v4, s38, 8, v245
	v_ashrrev_i32_e32 v5, 31, v4
	v_lshlrev_b64 v[4:5], 7, v[4:5]
	v_lshl_add_u64 v[20:21], s[8:9], 0, v[4:5]
	global_load_dwordx4 v[4:7], v[20:21], off offset:48
	global_load_dwordx4 v[8:11], v[20:21], off offset:32
	global_load_dwordx4 v[12:15], v[20:21], off
	global_load_dwordx4 v[16:19], v[20:21], off offset:16
	s_lshl_b32 s30, s61, 10
	s_and_b32 s30, s30, 0x1c00
	s_waitcnt vmcnt(0)
	v_pk_add_f32 v[14:15], v[14:15], v[18:19]
	v_pk_add_f32 v[12:13], v[12:13], v[16:17]
	v_pk_add_f32 v[10:11], v[14:15], v[10:11]
	v_pk_add_f32 v[8:9], v[12:13], v[8:9]
	v_pk_add_f32 v[22:23], v[10:11], v[6:7]
	v_pk_add_f32 v[24:25], v[8:9], v[4:5]
	global_load_dwordx4 v[4:7], v[20:21], off offset:112
	global_load_dwordx4 v[8:11], v[20:21], off offset:96
	global_load_dwordx4 v[12:15], v[20:21], off offset:80
	global_load_dwordx4 v[16:19], v[20:21], off offset:64
	s_waitcnt vmcnt(0)
	v_pk_add_f32 v[16:17], v[24:25], v[16:17]
	v_pk_add_f32 v[18:19], v[22:23], v[18:19]
	v_pk_add_f32 v[12:13], v[16:17], v[12:13]
	v_pk_add_f32 v[14:15], v[18:19], v[14:15]
	v_pk_add_f32 v[8:9], v[12:13], v[8:9]
	v_pk_add_f32 v[10:11], v[14:15], v[10:11]
	v_pk_add_f32 v[4:5], v[8:9], v[4:5]
	v_pk_add_f32 v[6:7], v[10:11], v[6:7]
	v_add_f32_e32 v4, v4, v5
	v_add_f32_e32 v4, v6, v4
	v_add_f32_e32 v4, v7, v4
	v_fmamk_f32 v4, v4, 0x3a000000, v197
	v_cmp_gt_f32_e32 vcc, s75, v4
	v_mul_f32_e32 v5, 0x4b800000, v4
	s_nop 0
	v_cndmask_b32_e32 v4, v4, v5, vcc
	v_rsq_f32_e32 v4, v4
	s_nop 0
	v_mul_f32_e32 v5, 0x45800000, v4
	v_cndmask_b32_e32 v4, v4, v5, vcc
	v_add_u32_e32 v5, s30, v146
	ds_write_b32 v5, v4
	s_branch .LBB0_422
